# GEMM epilogue stores marked nt (non-temporal) to shorten the barrier write-back
# baseline (speedup 1.0000x reference)
.LBB0_148:
	v_mul_f32_e32 v147, 0xbfb8aa3b, v124
	v_exp_f32_e32 v147, v147
	v_lshl_add_u32 v146, s54, 8, v142
	v_lshl_or_b32 v140, s53, 7, v144
	v_ashrrev_i32_e32 v141, 31, v140
	v_add_f32_e32 v147, 1.0, v147
	v_rcp_f32_e32 v150, v147
	v_mul_f32_e32 v147, 0xbfb8aa3b, v125
	v_exp_f32_e32 v147, v147
	v_mov_b64_e32 v[138:139], s[20:21]
	v_mad_i64_i32 v[148:149], s[18:19], v146, s82, v[138:139]
	v_add_f32_e32 v147, 1.0, v147
	v_rcp_f32_e32 v151, v147
	v_lshlrev_b64 v[140:141], 1, v[140:141]
	v_lshl_add_u64 v[148:149], v[148:149], 0, v[140:141]
	s_andn2_b64 vcc, exec, s[0:1]
	v_pk_mul_f32 v[124:125], v[124:125], v[150:151]
	s_mov_b32 s87, 0x9000
	v_pk_mul_f32 v[120:121], v[124:125], v[120:121]
	s_movk_i32 s86, 0x4000
	v_cvt_pk_bf16_f32 v120, v120, v121
	v_mul_f32_e32 v121, 0xbfb8aa3b, v126
	v_exp_f32_e32 v121, v121
	s_movk_i32 s72, 0x2000
	s_mov_b32 s73, 0x14000
	v_add_f32_e32 v121, 1.0, v121
	v_rcp_f32_e32 v124, v121
	v_mul_f32_e32 v121, 0xbfb8aa3b, v127
	v_exp_f32_e32 v121, v121
	s_nop 0
	v_add_f32_e32 v121, 1.0, v121
	v_rcp_f32_e32 v125, v121
	s_nop 0
	v_pk_mul_f32 v[124:125], v[126:127], v[124:125]
	s_nop 0
	v_pk_mul_f32 v[122:123], v[124:125], v[122:123]
	s_nop 0
	v_cvt_pk_bf16_f32 v121, v122, v123
	v_mul_f32_e32 v122, 0xbfb8aa3b, v116
	v_mul_f32_e32 v123, 0xbfb8aa3b, v117
	v_exp_f32_e32 v122, v122
	v_exp_f32_e32 v123, v123
	v_add_f32_e32 v122, 1.0, v122
	v_add_f32_e32 v123, 1.0, v123
	v_rcp_f32_e32 v122, v122
	v_rcp_f32_e32 v123, v123
	s_nop 0
	v_pk_mul_f32 v[116:117], v[116:117], v[122:123]
	s_nop 0
	v_pk_mul_f32 v[112:113], v[116:117], v[112:113]
	s_nop 0
	v_cvt_pk_bf16_f32 v122, v112, v113
	v_mul_f32_e32 v112, 0xbfb8aa3b, v118
	v_mul_f32_e32 v113, 0xbfb8aa3b, v119
	v_exp_f32_e32 v112, v112
	v_exp_f32_e32 v113, v113
	v_add_f32_e32 v112, 1.0, v112
	v_add_f32_e32 v113, 1.0, v113
	v_rcp_f32_e32 v112, v112
	v_rcp_f32_e32 v113, v113
	s_nop 0
	v_pk_mul_f32 v[112:113], v[118:119], v[112:113]
	s_nop 0
	v_pk_mul_f32 v[112:113], v[112:113], v[114:115]
	v_mul_f32_e32 v114, 0xbfb8aa3b, v108
	v_mul_f32_e32 v115, 0xbfb8aa3b, v109
	v_exp_f32_e32 v114, v114
	v_exp_f32_e32 v115, v115
	v_cvt_pk_bf16_f32 v123, v112, v113
	v_or_b32_e32 v112, 16, v146
	v_add_f32_e32 v114, 1.0, v114
	v_add_f32_e32 v115, 1.0, v115
	v_rcp_f32_e32 v114, v114
	v_rcp_f32_e32 v115, v115
	v_mad_i64_i32 v[112:113], s[18:19], v112, s82, v[138:139]
	v_lshl_add_u64 v[112:113], v[112:113], 0, v[140:141]
	v_pk_mul_f32 v[108:109], v[108:109], v[114:115]
	global_store_dwordx4 v[148:149], v[120:123], off nt
	v_pk_mul_f32 v[104:105], v[108:109], v[104:105]
	s_nop 0
	v_cvt_pk_bf16_f32 v104, v104, v105
	v_mul_f32_e32 v105, 0xbfb8aa3b, v110
	v_exp_f32_e32 v105, v105
	s_nop 0
	v_add_f32_e32 v105, 1.0, v105
	v_rcp_f32_e32 v108, v105
	v_mul_f32_e32 v105, 0xbfb8aa3b, v111
	v_exp_f32_e32 v105, v105
	s_nop 0
	v_add_f32_e32 v105, 1.0, v105
	v_rcp_f32_e32 v109, v105
	s_nop 0
	v_pk_mul_f32 v[108:109], v[110:111], v[108:109]
	s_nop 0
	v_pk_mul_f32 v[106:107], v[108:109], v[106:107]
	s_nop 0
	v_cvt_pk_bf16_f32 v105, v106, v107
	v_mul_f32_e32 v106, 0xbfb8aa3b, v100
	v_mul_f32_e32 v107, 0xbfb8aa3b, v101
	v_exp_f32_e32 v106, v106
	v_exp_f32_e32 v107, v107
	v_add_f32_e32 v106, 1.0, v106
	v_add_f32_e32 v107, 1.0, v107
	v_rcp_f32_e32 v106, v106
	v_rcp_f32_e32 v107, v107
	s_nop 0
	v_pk_mul_f32 v[100:101], v[100:101], v[106:107]
	s_nop 0
	v_pk_mul_f32 v[96:97], v[100:101], v[96:97]
	s_nop 0
	v_cvt_pk_bf16_f32 v106, v96, v97
	v_mul_f32_e32 v96, 0xbfb8aa3b, v102
	v_mul_f32_e32 v97, 0xbfb8aa3b, v103
	v_exp_f32_e32 v96, v96
	v_exp_f32_e32 v97, v97
	v_add_f32_e32 v96, 1.0, v96
	v_add_f32_e32 v97, 1.0, v97
	v_rcp_f32_e32 v96, v96
	v_rcp_f32_e32 v97, v97
	s_nop 0
	v_pk_mul_f32 v[96:97], v[102:103], v[96:97]
	s_nop 0
	v_pk_mul_f32 v[96:97], v[96:97], v[98:99]
	v_mul_f32_e32 v98, 0xbfb8aa3b, v92
	v_mul_f32_e32 v99, 0xbfb8aa3b, v93
	v_exp_f32_e32 v98, v98
	v_exp_f32_e32 v99, v99
	v_cvt_pk_bf16_f32 v107, v96, v97
	v_or_b32_e32 v96, 32, v146
	v_add_f32_e32 v98, 1.0, v98
	v_add_f32_e32 v99, 1.0, v99
	v_rcp_f32_e32 v98, v98
	v_rcp_f32_e32 v99, v99
	v_mad_i64_i32 v[96:97], s[18:19], v96, s82, v[138:139]
	v_lshl_add_u64 v[96:97], v[96:97], 0, v[140:141]
	v_pk_mul_f32 v[92:93], v[92:93], v[98:99]
	global_store_dwordx4 v[112:113], v[104:107], off nt
	v_pk_mul_f32 v[88:89], v[92:93], v[88:89]
	s_nop 0
	v_cvt_pk_bf16_f32 v88, v88, v89
	v_mul_f32_e32 v89, 0xbfb8aa3b, v94
	v_exp_f32_e32 v89, v89
	s_nop 0
	v_add_f32_e32 v89, 1.0, v89
	v_rcp_f32_e32 v92, v89
	v_mul_f32_e32 v89, 0xbfb8aa3b, v95
	v_exp_f32_e32 v89, v89
	s_nop 0
	v_add_f32_e32 v89, 1.0, v89
	v_rcp_f32_e32 v93, v89
	s_nop 0
	v_pk_mul_f32 v[92:93], v[94:95], v[92:93]
	s_nop 0
	v_pk_mul_f32 v[90:91], v[92:93], v[90:91]
	s_nop 0
	v_cvt_pk_bf16_f32 v89, v90, v91
	v_mul_f32_e32 v90, 0xbfb8aa3b, v84
	v_mul_f32_e32 v91, 0xbfb8aa3b, v85
	v_exp_f32_e32 v90, v90
	v_exp_f32_e32 v91, v91
	v_add_f32_e32 v90, 1.0, v90
	v_add_f32_e32 v91, 1.0, v91
	v_rcp_f32_e32 v90, v90
	v_rcp_f32_e32 v91, v91
	s_nop 0
	v_pk_mul_f32 v[84:85], v[84:85], v[90:91]
	s_nop 0
	v_pk_mul_f32 v[80:81], v[84:85], v[80:81]
	s_nop 0
	v_cvt_pk_bf16_f32 v90, v80, v81
	v_mul_f32_e32 v80, 0xbfb8aa3b, v86
	v_mul_f32_e32 v81, 0xbfb8aa3b, v87
	v_exp_f32_e32 v80, v80
	v_exp_f32_e32 v81, v81
	v_add_f32_e32 v80, 1.0, v80
	v_add_f32_e32 v81, 1.0, v81
	v_rcp_f32_e32 v80, v80
	v_rcp_f32_e32 v81, v81
	s_nop 0
	v_pk_mul_f32 v[80:81], v[86:87], v[80:81]
	s_nop 0
	v_pk_mul_f32 v[80:81], v[80:81], v[82:83]
	v_mul_f32_e32 v82, 0xbfb8aa3b, v76
	v_mul_f32_e32 v83, 0xbfb8aa3b, v77
	v_exp_f32_e32 v82, v82
	v_exp_f32_e32 v83, v83
	v_cvt_pk_bf16_f32 v91, v80, v81
	v_or_b32_e32 v80, 48, v146
	v_add_f32_e32 v82, 1.0, v82
	v_add_f32_e32 v83, 1.0, v83
	v_rcp_f32_e32 v82, v82
	v_rcp_f32_e32 v83, v83
	v_mad_i64_i32 v[80:81], s[18:19], v80, s82, v[138:139]
	v_lshl_add_u64 v[80:81], v[80:81], 0, v[140:141]
	v_pk_mul_f32 v[76:77], v[76:77], v[82:83]
	global_store_dwordx4 v[96:97], v[88:91], off nt
	v_pk_mul_f32 v[72:73], v[76:77], v[72:73]
	s_nop 0
	v_cvt_pk_bf16_f32 v72, v72, v73
	v_mul_f32_e32 v73, 0xbfb8aa3b, v78
	v_exp_f32_e32 v73, v73
	s_nop 0
	v_add_f32_e32 v73, 1.0, v73
	v_rcp_f32_e32 v76, v73
	v_mul_f32_e32 v73, 0xbfb8aa3b, v79
	v_exp_f32_e32 v73, v73
	s_nop 0
	v_add_f32_e32 v73, 1.0, v73
	v_rcp_f32_e32 v77, v73
	s_nop 0
	v_pk_mul_f32 v[76:77], v[78:79], v[76:77]
	s_nop 0
	v_pk_mul_f32 v[74:75], v[76:77], v[74:75]
	s_nop 0
	v_cvt_pk_bf16_f32 v73, v74, v75
	v_mul_f32_e32 v74, 0xbfb8aa3b, v68
	v_mul_f32_e32 v75, 0xbfb8aa3b, v69
	v_exp_f32_e32 v74, v74
	v_exp_f32_e32 v75, v75
	v_add_f32_e32 v74, 1.0, v74
	v_add_f32_e32 v75, 1.0, v75
	v_rcp_f32_e32 v74, v74
	v_rcp_f32_e32 v75, v75
	s_nop 0
	v_pk_mul_f32 v[68:69], v[68:69], v[74:75]
	s_nop 0
	v_pk_mul_f32 v[64:65], v[68:69], v[64:65]
	s_nop 0
	v_cvt_pk_bf16_f32 v74, v64, v65
	v_mul_f32_e32 v64, 0xbfb8aa3b, v70
	v_mul_f32_e32 v65, 0xbfb8aa3b, v71
	v_exp_f32_e32 v64, v64
	v_exp_f32_e32 v65, v65
	v_add_f32_e32 v64, 1.0, v64
	v_add_f32_e32 v65, 1.0, v65
	v_rcp_f32_e32 v64, v64
	v_rcp_f32_e32 v65, v65
	s_nop 0
	v_pk_mul_f32 v[64:65], v[70:71], v[64:65]
	s_nop 0
	v_pk_mul_f32 v[64:65], v[64:65], v[66:67]
	v_mul_f32_e32 v66, 0xbfb8aa3b, v60
	v_mul_f32_e32 v67, 0xbfb8aa3b, v61
	v_exp_f32_e32 v66, v66
	v_exp_f32_e32 v67, v67
	v_cvt_pk_bf16_f32 v75, v64, v65
	v_add_u32_e32 v64, 0x80, v146
	v_add_f32_e32 v66, 1.0, v66
	v_add_f32_e32 v67, 1.0, v67
	v_rcp_f32_e32 v66, v66
	v_rcp_f32_e32 v67, v67
	v_mad_i64_i32 v[64:65], s[18:19], v64, s82, v[138:139]
	v_lshl_add_u64 v[64:65], v[64:65], 0, v[140:141]
	v_pk_mul_f32 v[60:61], v[60:61], v[66:67]
	global_store_dwordx4 v[80:81], v[72:75], off nt
	v_pk_mul_f32 v[56:57], v[60:61], v[56:57]
	s_nop 0
	v_cvt_pk_bf16_f32 v56, v56, v57
	v_mul_f32_e32 v57, 0xbfb8aa3b, v62
	v_exp_f32_e32 v57, v57
	s_nop 0
	v_add_f32_e32 v57, 1.0, v57
	v_rcp_f32_e32 v60, v57
	v_mul_f32_e32 v57, 0xbfb8aa3b, v63
	v_exp_f32_e32 v57, v57
	s_nop 0
	v_add_f32_e32 v57, 1.0, v57
	v_rcp_f32_e32 v61, v57
	s_nop 0
	v_pk_mul_f32 v[60:61], v[62:63], v[60:61]
	s_nop 0
	v_pk_mul_f32 v[58:59], v[60:61], v[58:59]
	s_nop 0
	v_cvt_pk_bf16_f32 v57, v58, v59
	v_mul_f32_e32 v58, 0xbfb8aa3b, v52
	v_mul_f32_e32 v59, 0xbfb8aa3b, v53
	v_exp_f32_e32 v58, v58
	v_exp_f32_e32 v59, v59
	v_add_f32_e32 v58, 1.0, v58
	v_add_f32_e32 v59, 1.0, v59
	v_rcp_f32_e32 v58, v58
	v_rcp_f32_e32 v59, v59
	s_nop 0
	v_pk_mul_f32 v[52:53], v[52:53], v[58:59]
	s_nop 0
	v_pk_mul_f32 v[48:49], v[52:53], v[48:49]
	s_nop 0
	v_cvt_pk_bf16_f32 v58, v48, v49
	v_mul_f32_e32 v48, 0xbfb8aa3b, v54
	v_mul_f32_e32 v49, 0xbfb8aa3b, v55
	v_exp_f32_e32 v48, v48
	v_exp_f32_e32 v49, v49
	v_add_f32_e32 v48, 1.0, v48
	v_add_f32_e32 v49, 1.0, v49
	v_rcp_f32_e32 v48, v48
	v_rcp_f32_e32 v49, v49
	s_nop 0
	v_pk_mul_f32 v[48:49], v[54:55], v[48:49]
	s_nop 0
	v_pk_mul_f32 v[48:49], v[48:49], v[50:51]
	v_mul_f32_e32 v50, 0xbfb8aa3b, v44
	v_mul_f32_e32 v51, 0xbfb8aa3b, v45
	v_exp_f32_e32 v50, v50
	v_exp_f32_e32 v51, v51
	v_cvt_pk_bf16_f32 v59, v48, v49
	v_add_u32_e32 v48, 0x90, v146
	v_add_f32_e32 v50, 1.0, v50
	v_add_f32_e32 v51, 1.0, v51
	v_rcp_f32_e32 v50, v50
	v_rcp_f32_e32 v51, v51
	v_mad_i64_i32 v[48:49], s[18:19], v48, s82, v[138:139]
	v_lshl_add_u64 v[48:49], v[48:49], 0, v[140:141]
	v_pk_mul_f32 v[44:45], v[44:45], v[50:51]
	global_store_dwordx4 v[64:65], v[56:59], off nt
	v_pk_mul_f32 v[40:41], v[44:45], v[40:41]
	s_nop 0
	v_cvt_pk_bf16_f32 v40, v40, v41
	v_mul_f32_e32 v41, 0xbfb8aa3b, v46
	v_exp_f32_e32 v41, v41
	s_nop 0
	v_add_f32_e32 v41, 1.0, v41
	v_rcp_f32_e32 v44, v41
	v_mul_f32_e32 v41, 0xbfb8aa3b, v47
	v_exp_f32_e32 v41, v41
	s_nop 0
	v_add_f32_e32 v41, 1.0, v41
	v_rcp_f32_e32 v45, v41
	s_nop 0
	v_pk_mul_f32 v[44:45], v[46:47], v[44:45]
	s_nop 0
	v_pk_mul_f32 v[42:43], v[44:45], v[42:43]
	s_nop 0
	v_cvt_pk_bf16_f32 v41, v42, v43
	v_mul_f32_e32 v42, 0xbfb8aa3b, v36
	v_mul_f32_e32 v43, 0xbfb8aa3b, v37
	v_exp_f32_e32 v42, v42
	v_exp_f32_e32 v43, v43
	v_add_f32_e32 v42, 1.0, v42
	v_add_f32_e32 v43, 1.0, v43
	v_rcp_f32_e32 v42, v42
	v_rcp_f32_e32 v43, v43
	s_nop 0
	v_pk_mul_f32 v[36:37], v[36:37], v[42:43]
	s_nop 0
	v_pk_mul_f32 v[32:33], v[36:37], v[32:33]
	s_nop 0
	v_cvt_pk_bf16_f32 v42, v32, v33
	v_mul_f32_e32 v32, 0xbfb8aa3b, v38
	v_mul_f32_e32 v33, 0xbfb8aa3b, v39
	v_exp_f32_e32 v32, v32
	v_exp_f32_e32 v33, v33
	v_add_f32_e32 v32, 1.0, v32
	v_add_f32_e32 v33, 1.0, v33
	v_rcp_f32_e32 v32, v32
	v_rcp_f32_e32 v33, v33
	s_nop 0
	v_pk_mul_f32 v[32:33], v[38:39], v[32:33]
	s_nop 0
	v_pk_mul_f32 v[32:33], v[32:33], v[34:35]
	v_mul_f32_e32 v34, 0xbfb8aa3b, v28
	v_mul_f32_e32 v35, 0xbfb8aa3b, v29
	v_exp_f32_e32 v34, v34
	v_exp_f32_e32 v35, v35
	v_cvt_pk_bf16_f32 v43, v32, v33
	v_add_u32_e32 v32, 0xa0, v146
	v_add_f32_e32 v34, 1.0, v34
	v_add_f32_e32 v35, 1.0, v35
	v_rcp_f32_e32 v34, v34
	v_rcp_f32_e32 v35, v35
	v_mad_i64_i32 v[32:33], s[18:19], v32, s82, v[138:139]
	v_lshl_add_u64 v[32:33], v[32:33], 0, v[140:141]
	v_pk_mul_f32 v[28:29], v[28:29], v[34:35]
	global_store_dwordx4 v[48:49], v[40:43], off nt
	v_pk_mul_f32 v[24:25], v[28:29], v[24:25]
	s_nop 0
	v_cvt_pk_bf16_f32 v24, v24, v25
	v_mul_f32_e32 v25, 0xbfb8aa3b, v30
	v_exp_f32_e32 v25, v25
	s_nop 0
	v_add_f32_e32 v25, 1.0, v25
	v_rcp_f32_e32 v28, v25
	v_mul_f32_e32 v25, 0xbfb8aa3b, v31
	v_exp_f32_e32 v25, v25
	s_nop 0
	v_add_f32_e32 v25, 1.0, v25
	v_rcp_f32_e32 v29, v25
	s_nop 0
	v_pk_mul_f32 v[28:29], v[30:31], v[28:29]
	s_nop 0
	v_pk_mul_f32 v[26:27], v[28:29], v[26:27]
	s_nop 0
	v_cvt_pk_bf16_f32 v25, v26, v27
	v_mul_f32_e32 v26, 0xbfb8aa3b, v20
	v_mul_f32_e32 v27, 0xbfb8aa3b, v21
	v_exp_f32_e32 v26, v26
	v_exp_f32_e32 v27, v27
	v_add_f32_e32 v26, 1.0, v26
	v_add_f32_e32 v27, 1.0, v27
	v_rcp_f32_e32 v26, v26
	v_rcp_f32_e32 v27, v27
	s_nop 0
	v_pk_mul_f32 v[20:21], v[20:21], v[26:27]
	s_nop 0
	v_pk_mul_f32 v[16:17], v[20:21], v[16:17]
	s_nop 0
	v_cvt_pk_bf16_f32 v26, v16, v17
	v_mul_f32_e32 v16, 0xbfb8aa3b, v22
	v_mul_f32_e32 v17, 0xbfb8aa3b, v23
	v_exp_f32_e32 v16, v16
	v_exp_f32_e32 v17, v17
	v_add_f32_e32 v16, 1.0, v16
	v_add_f32_e32 v17, 1.0, v17
	v_rcp_f32_e32 v16, v16
	v_rcp_f32_e32 v17, v17
	s_nop 0
	v_pk_mul_f32 v[16:17], v[22:23], v[16:17]
	s_nop 0
	v_pk_mul_f32 v[16:17], v[16:17], v[18:19]
	v_mul_f32_e32 v18, 0xbfb8aa3b, v12
	v_mul_f32_e32 v19, 0xbfb8aa3b, v13
	v_exp_f32_e32 v18, v18
	v_exp_f32_e32 v19, v19
	v_cvt_pk_bf16_f32 v27, v16, v17
	v_add_u32_e32 v16, 0xb0, v146
	v_add_f32_e32 v18, 1.0, v18
	v_add_f32_e32 v19, 1.0, v19
	v_rcp_f32_e32 v18, v18
	v_rcp_f32_e32 v19, v19
	v_mad_i64_i32 v[16:17], s[18:19], v16, s82, v[138:139]
	v_lshl_add_u64 v[16:17], v[16:17], 0, v[140:141]
	v_pk_mul_f32 v[12:13], v[12:13], v[18:19]
	s_mov_b64 s[18:19], -1
	v_pk_mul_f32 v[8:9], v[12:13], v[8:9]
	global_store_dwordx4 v[32:33], v[24:27], off nt
	v_cvt_pk_bf16_f32 v8, v8, v9
	v_mul_f32_e32 v9, 0xbfb8aa3b, v14
	v_exp_f32_e32 v9, v9
	s_nop 0
	v_add_f32_e32 v9, 1.0, v9
	v_rcp_f32_e32 v12, v9
	v_mul_f32_e32 v9, 0xbfb8aa3b, v15
	v_exp_f32_e32 v9, v9
	s_nop 0
	v_add_f32_e32 v9, 1.0, v9
	v_rcp_f32_e32 v13, v9
	s_nop 0
	v_pk_mul_f32 v[12:13], v[14:15], v[12:13]
	s_nop 0
	v_pk_mul_f32 v[10:11], v[12:13], v[10:11]
	s_nop 0
	v_cvt_pk_bf16_f32 v9, v10, v11
	v_mul_f32_e32 v10, 0xbfb8aa3b, v4
	v_mul_f32_e32 v11, 0xbfb8aa3b, v5
	v_exp_f32_e32 v10, v10
	v_exp_f32_e32 v11, v11
	v_add_f32_e32 v10, 1.0, v10
	v_add_f32_e32 v11, 1.0, v11
	v_rcp_f32_e32 v10, v10
	v_rcp_f32_e32 v11, v11
	s_nop 0
	v_pk_mul_f32 v[4:5], v[4:5], v[10:11]
	s_nop 0
	v_pk_mul_f32 v[0:1], v[4:5], v[0:1]
	s_nop 0
	v_cvt_pk_bf16_f32 v10, v0, v1
	v_mul_f32_e32 v0, 0xbfb8aa3b, v6
	v_mul_f32_e32 v1, 0xbfb8aa3b, v7
	v_exp_f32_e32 v0, v0
	v_exp_f32_e32 v1, v1
	v_add_f32_e32 v0, 1.0, v0
	v_add_f32_e32 v1, 1.0, v1
	v_rcp_f32_e32 v0, v0
	v_rcp_f32_e32 v1, v1
	s_nop 0
	v_pk_mul_f32 v[0:1], v[6:7], v[0:1]
	s_nop 0
	v_pk_mul_f32 v[0:1], v[0:1], v[2:3]
	s_nop 0
	v_cvt_pk_bf16_f32 v11, v0, v1
	global_store_dwordx4 v[16:17], v[8:11], off nt
	s_cbranch_vccnz .LBB0_141
	s_andn2_b64 vcc, exec, s[4:5]
	s_cbranch_vccnz .LBB0_140
	s_barrier
	s_branch .LBB0_140

.LBB0_224:
	s_ashr_i32 s14, s55, 3
	s_mul_hi_i32 s15, s14, 0x9000
	s_mul_i32 s14, s14, 0x9000
	v_lshl_or_b32 v134, s58, 8, v144
	s_add_u32 s14, s48, s14
	s_addc_u32 s15, s49, s15
	v_ashrrev_i32_e32 v135, 31, v134
	v_lshl_add_u32 v140, s55, 8, v142
	v_lshl_add_u64 v[136:137], v[134:135], 2, s[14:15]
	v_ashrrev_i32_e32 v141, 31, v140
	global_load_dwordx4 v[146:149], v[136:137], off
	v_lshlrev_b64 v[138:139], 10, v[140:141]
	v_lshl_add_u64 v[138:139], v[138:139], 0, v[134:135]
	v_lshlrev_b64 v[138:139], 2, v[138:139]
	v_lshl_add_u64 v[154:155], s[6:7], 0, v[138:139]
	global_load_dwordx4 v[150:153], v[154:155], off
	global_load_dwordx4 v[188:191], v[154:155], off offset:64
	global_load_dwordx4 v[192:195], v[154:155], off offset:512
	global_load_dwordx4 v[196:199], v[154:155], off offset:576
	global_load_dwordx4 v[172:175], v[136:137], off offset:64
	global_load_dwordx4 v[180:183], v[136:137], off offset:512
	global_load_dwordx4 v[184:187], v[136:137], off offset:576
	v_lshl_add_u64 v[176:177], s[26:27], 0, v[138:139]
	s_and_b64 vcc, exec, s[0:1]
	s_mov_b64 s[0:1], -1
	s_mov_b32 s87, 0x9000
	s_movk_i32 s86, 0x4000
	s_movk_i32 s72, 0x2000
	s_mov_b32 s73, 0x14000
	s_waitcnt vmcnt(0)
	v_pk_mul_f32 v[136:137], v[148:149], 0.5 op_sel_hi:[1,0]
	v_pk_mul_f32 v[138:139], v[146:147], 0.5 op_sel_hi:[1,0]
	v_pk_fma_f32 v[126:127], v[126:127], v[136:137], v[152:153]
	v_pk_fma_f32 v[124:125], v[124:125], v[138:139], v[150:151]
	global_store_dwordx4 v[176:177], v[124:127], off nt
	s_nop 1
	s_nop 0
	v_pk_mul_f32 v[124:125], v[174:175], 0.5 op_sel_hi:[1,0]
	v_pk_mul_f32 v[126:127], v[172:173], 0.5 op_sel_hi:[1,0]
	v_pk_fma_f32 v[122:123], v[122:123], v[124:125], v[190:191]
	v_pk_fma_f32 v[120:121], v[120:121], v[126:127], v[188:189]
	global_store_dwordx4 v[176:177], v[120:123], off offset:64 nt
	s_nop 1
	s_nop 0
	v_pk_mul_f32 v[120:121], v[182:183], 0.5 op_sel_hi:[1,0]
	v_pk_mul_f32 v[122:123], v[180:181], 0.5 op_sel_hi:[1,0]
	v_pk_fma_f32 v[118:119], v[118:119], v[120:121], v[194:195]
	v_pk_fma_f32 v[116:117], v[116:117], v[122:123], v[192:193]
	global_store_dwordx4 v[176:177], v[116:119], off offset:512 nt
	s_nop 1
	s_nop 0
	v_or_b32_e32 v116, 16, v140
	v_ashrrev_i32_e32 v117, 31, v116
	v_lshlrev_b64 v[116:117], 10, v[116:117]
	v_lshl_add_u64 v[116:117], v[116:117], 0, v[134:135]
	v_lshlrev_b64 v[150:151], 2, v[116:117]
	v_pk_mul_f32 v[116:117], v[186:187], 0.5 op_sel_hi:[1,0]
	v_pk_mul_f32 v[118:119], v[184:185], 0.5 op_sel_hi:[1,0]
	v_lshl_add_u64 v[152:153], s[6:7], 0, v[150:151]
	v_pk_fma_f32 v[106:107], v[106:107], v[116:117], v[198:199]
	v_pk_fma_f32 v[104:105], v[104:105], v[118:119], v[196:197]
	global_store_dwordx4 v[176:177], v[104:107], off offset:576 nt
	global_load_dwordx4 v[104:107], v[152:153], off
	global_load_dwordx4 v[188:191], v[152:153], off offset:64
	global_load_dwordx4 v[192:195], v[152:153], off offset:512
	global_load_dwordx4 v[196:199], v[152:153], off offset:576
	v_lshl_add_u64 v[146:147], s[26:27], 0, v[150:151]
	s_waitcnt vmcnt(0)
	v_pk_fma_f32 v[106:107], v[114:115], v[136:137], v[106:107]
	v_pk_fma_f32 v[104:105], v[112:113], v[138:139], v[104:105]
	global_store_dwordx4 v[146:147], v[104:107], off nt
	v_pk_fma_f32 v[190:191], v[110:111], v[124:125], v[190:191]
	v_pk_fma_f32 v[188:189], v[108:109], v[126:127], v[188:189]
	global_store_dwordx4 v[146:147], v[188:191], off offset:64 nt
	v_pk_fma_f32 v[102:103], v[102:103], v[120:121], v[194:195]
	v_pk_fma_f32 v[100:101], v[100:101], v[122:123], v[192:193]
	global_store_dwordx4 v[146:147], v[100:103], off offset:512 nt
	v_or_b32_e32 v104, 32, v140
	v_ashrrev_i32_e32 v105, 31, v104
	v_lshlrev_b64 v[104:105], 10, v[104:105]
	v_lshl_add_u64 v[104:105], v[104:105], 0, v[134:135]
	v_lshlrev_b64 v[104:105], 2, v[104:105]
	v_lshl_add_u64 v[106:107], s[6:7], 0, v[104:105]
	v_pk_fma_f32 v[90:91], v[90:91], v[116:117], v[198:199]
	v_pk_fma_f32 v[88:89], v[88:89], v[118:119], v[196:197]
	global_store_dwordx4 v[146:147], v[88:91], off offset:576 nt
	global_load_dwordx4 v[88:91], v[106:107], off
	global_load_dwordx4 v[188:191], v[106:107], off offset:64
	global_load_dwordx4 v[192:195], v[106:107], off offset:512
	global_load_dwordx4 v[196:199], v[106:107], off offset:576
	v_lshl_add_u64 v[100:101], s[26:27], 0, v[104:105]
	s_waitcnt vmcnt(0)
	v_pk_fma_f32 v[90:91], v[98:99], v[136:137], v[90:91]
	v_pk_fma_f32 v[88:89], v[96:97], v[138:139], v[88:89]
	global_store_dwordx4 v[100:101], v[88:91], off nt
	v_pk_fma_f32 v[190:191], v[94:95], v[124:125], v[190:191]
	v_pk_fma_f32 v[188:189], v[92:93], v[126:127], v[188:189]
	global_store_dwordx4 v[100:101], v[188:191], off offset:64 nt
	v_pk_fma_f32 v[86:87], v[86:87], v[120:121], v[194:195]
	v_pk_fma_f32 v[84:85], v[84:85], v[122:123], v[192:193]
	global_store_dwordx4 v[100:101], v[84:87], off offset:512 nt
	v_or_b32_e32 v88, 48, v140
	v_ashrrev_i32_e32 v89, 31, v88
	v_lshlrev_b64 v[88:89], 10, v[88:89]
	v_lshl_add_u64 v[88:89], v[88:89], 0, v[134:135]
	v_lshlrev_b64 v[88:89], 2, v[88:89]
	v_lshl_add_u64 v[90:91], s[6:7], 0, v[88:89]
	v_pk_fma_f32 v[74:75], v[74:75], v[116:117], v[198:199]
	v_pk_fma_f32 v[72:73], v[72:73], v[118:119], v[196:197]
	global_store_dwordx4 v[100:101], v[72:75], off offset:576 nt
	global_load_dwordx4 v[72:75], v[90:91], off
	global_load_dwordx4 v[188:191], v[90:91], off offset:64
	global_load_dwordx4 v[192:195], v[90:91], off offset:512
	global_load_dwordx4 v[196:199], v[90:91], off offset:576
	v_lshl_add_u64 v[84:85], s[26:27], 0, v[88:89]
	s_waitcnt vmcnt(0)
	v_pk_fma_f32 v[74:75], v[82:83], v[136:137], v[74:75]
	v_pk_fma_f32 v[72:73], v[80:81], v[138:139], v[72:73]
	global_store_dwordx4 v[84:85], v[72:75], off nt
	v_pk_fma_f32 v[190:191], v[78:79], v[124:125], v[190:191]
	v_pk_fma_f32 v[188:189], v[76:77], v[126:127], v[188:189]
	global_store_dwordx4 v[84:85], v[188:191], off offset:64 nt
	v_pk_fma_f32 v[70:71], v[70:71], v[120:121], v[194:195]
	v_pk_fma_f32 v[68:69], v[68:69], v[122:123], v[192:193]
	global_store_dwordx4 v[84:85], v[68:71], off offset:512 nt
	v_add_u32_e32 v72, 0x80, v140
	v_ashrrev_i32_e32 v73, 31, v72
	v_lshlrev_b64 v[72:73], 10, v[72:73]
	v_lshl_add_u64 v[72:73], v[72:73], 0, v[134:135]
	v_lshlrev_b64 v[72:73], 2, v[72:73]
	v_lshl_add_u64 v[74:75], s[6:7], 0, v[72:73]
	v_pk_fma_f32 v[66:67], v[66:67], v[116:117], v[198:199]
	v_pk_fma_f32 v[64:65], v[64:65], v[118:119], v[196:197]
	global_store_dwordx4 v[84:85], v[64:67], off offset:576 nt
	global_load_dwordx4 v[64:67], v[74:75], off
	global_load_dwordx4 v[188:191], v[74:75], off offset:64
	global_load_dwordx4 v[192:195], v[74:75], off offset:512
	global_load_dwordx4 v[196:199], v[74:75], off offset:576
	v_lshl_add_u64 v[68:69], s[26:27], 0, v[72:73]
	s_waitcnt vmcnt(0)
	v_pk_fma_f32 v[62:63], v[62:63], v[136:137], v[66:67]
	v_pk_fma_f32 v[60:61], v[60:61], v[138:139], v[64:65]
	global_store_dwordx4 v[68:69], v[60:63], off nt
	v_pk_fma_f32 v[58:59], v[58:59], v[124:125], v[190:191]
	v_pk_fma_f32 v[56:57], v[56:57], v[126:127], v[188:189]
	global_store_dwordx4 v[68:69], v[56:59], off offset:64 nt
	v_pk_fma_f32 v[54:55], v[54:55], v[120:121], v[194:195]
	v_pk_fma_f32 v[52:53], v[52:53], v[122:123], v[192:193]
	global_store_dwordx4 v[68:69], v[52:55], off offset:512 nt
	v_add_u32_e32 v56, 0x90, v140
	v_ashrrev_i32_e32 v57, 31, v56
	v_lshlrev_b64 v[56:57], 10, v[56:57]
	v_lshl_add_u64 v[56:57], v[56:57], 0, v[134:135]
	v_lshlrev_b64 v[56:57], 2, v[56:57]
	v_lshl_add_u64 v[58:59], s[6:7], 0, v[56:57]
	v_pk_fma_f32 v[42:43], v[42:43], v[116:117], v[198:199]
	v_pk_fma_f32 v[40:41], v[40:41], v[118:119], v[196:197]
	global_store_dwordx4 v[68:69], v[40:43], off offset:576 nt
	global_load_dwordx4 v[40:43], v[58:59], off
	global_load_dwordx4 v[188:191], v[58:59], off offset:64
	global_load_dwordx4 v[192:195], v[58:59], off offset:512
	global_load_dwordx4 v[196:199], v[58:59], off offset:576
	v_lshl_add_u64 v[52:53], s[26:27], 0, v[56:57]
	s_waitcnt vmcnt(0)
	v_pk_fma_f32 v[42:43], v[50:51], v[136:137], v[42:43]
	v_pk_fma_f32 v[40:41], v[48:49], v[138:139], v[40:41]
	global_store_dwordx4 v[52:53], v[40:43], off nt
	v_pk_fma_f32 v[190:191], v[46:47], v[124:125], v[190:191]
	v_pk_fma_f32 v[188:189], v[44:45], v[126:127], v[188:189]
	global_store_dwordx4 v[52:53], v[188:191], off offset:64 nt
	v_pk_fma_f32 v[38:39], v[38:39], v[120:121], v[194:195]
	v_pk_fma_f32 v[36:37], v[36:37], v[122:123], v[192:193]
	global_store_dwordx4 v[52:53], v[36:39], off offset:512 nt
	v_add_u32_e32 v40, 0xa0, v140
	v_ashrrev_i32_e32 v41, 31, v40
	v_lshlrev_b64 v[40:41], 10, v[40:41]
	v_lshl_add_u64 v[40:41], v[40:41], 0, v[134:135]
	v_lshlrev_b64 v[40:41], 2, v[40:41]
	v_lshl_add_u64 v[42:43], s[6:7], 0, v[40:41]
	v_pk_fma_f32 v[26:27], v[26:27], v[116:117], v[198:199]
	v_pk_fma_f32 v[24:25], v[24:25], v[118:119], v[196:197]
	global_store_dwordx4 v[52:53], v[24:27], off offset:576 nt
	global_load_dwordx4 v[24:27], v[42:43], off
	global_load_dwordx4 v[188:191], v[42:43], off offset:64
	global_load_dwordx4 v[192:195], v[42:43], off offset:512
	global_load_dwordx4 v[196:199], v[42:43], off offset:576
	v_lshl_add_u64 v[36:37], s[26:27], 0, v[40:41]
	s_waitcnt vmcnt(0)
	v_pk_fma_f32 v[26:27], v[34:35], v[136:137], v[26:27]
	v_pk_fma_f32 v[24:25], v[32:33], v[138:139], v[24:25]
	global_store_dwordx4 v[36:37], v[24:27], off nt
	v_pk_fma_f32 v[190:191], v[30:31], v[124:125], v[190:191]
	v_pk_fma_f32 v[188:189], v[28:29], v[126:127], v[188:189]
	global_store_dwordx4 v[36:37], v[188:191], off offset:64 nt
	v_pk_fma_f32 v[22:23], v[22:23], v[120:121], v[194:195]
	v_pk_fma_f32 v[20:21], v[20:21], v[122:123], v[192:193]
	global_store_dwordx4 v[36:37], v[20:23], off offset:512 nt
	v_add_u32_e32 v24, 0xb0, v140
	v_ashrrev_i32_e32 v25, 31, v24
	v_lshlrev_b64 v[24:25], 10, v[24:25]
	v_lshl_add_u64 v[24:25], v[24:25], 0, v[134:135]
	v_lshlrev_b64 v[24:25], 2, v[24:25]
	v_lshl_add_u64 v[26:27], s[6:7], 0, v[24:25]
	v_pk_fma_f32 v[10:11], v[10:11], v[116:117], v[198:199]
	v_pk_fma_f32 v[8:9], v[8:9], v[118:119], v[196:197]
	global_store_dwordx4 v[36:37], v[8:11], off offset:576 nt
	global_load_dwordx4 v[8:11], v[26:27], off
	global_load_dwordx4 v[188:191], v[26:27], off offset:64
	global_load_dwordx4 v[192:195], v[26:27], off offset:512
	global_load_dwordx4 v[196:199], v[26:27], off offset:576
	v_lshl_add_u64 v[20:21], s[26:27], 0, v[24:25]
	s_waitcnt vmcnt(0)
	v_pk_fma_f32 v[10:11], v[18:19], v[136:137], v[10:11]
	v_pk_fma_f32 v[8:9], v[16:17], v[138:139], v[8:9]
	global_store_dwordx4 v[20:21], v[8:11], off nt
	v_pk_fma_f32 v[190:191], v[14:15], v[124:125], v[190:191]
	v_pk_fma_f32 v[188:189], v[12:13], v[126:127], v[188:189]
	global_store_dwordx4 v[20:21], v[188:191], off offset:64 nt
	v_pk_fma_f32 v[6:7], v[6:7], v[120:121], v[194:195]
	v_pk_fma_f32 v[4:5], v[4:5], v[122:123], v[192:193]
	global_store_dwordx4 v[20:21], v[4:7], off offset:512 nt
	v_pk_fma_f32 v[2:3], v[2:3], v[116:117], v[198:199]
	v_pk_fma_f32 v[0:1], v[0:1], v[118:119], v[196:197]
	global_store_dwordx4 v[20:21], v[0:3], off offset:576 nt
	s_cbranch_vccnz .LBB0_209
	s_andn2_b64 vcc, exec, s[8:9]
	s_cbranch_vccnz .LBB0_208
	s_barrier
	s_branch .LBB0_208

.LBB0_364:
	v_lshl_add_u32 v148, s52, 8, v138
	v_lshl_or_b32 v142, s51, 8, v140
	v_ashrrev_i32_e32 v143, 31, v142
	v_mov_b64_e32 v[144:145], s[20:21]
	v_cvt_pk_bf16_f32 v68, v68, v69
	v_cvt_pk_bf16_f32 v69, v70, v71
	v_cvt_pk_bf16_f32 v70, v64, v65
	v_add_u32_e32 v64, 0x80, v148
	v_mad_i64_i32 v[146:147], s[16:17], v148, s90, v[144:145]
	v_lshlrev_b64 v[142:143], 1, v[142:143]
	v_cvt_pk_bf16_f32 v108, v108, v109
	v_cvt_pk_bf16_f32 v109, v110, v111
	v_cvt_pk_bf16_f32 v110, v104, v105
	v_or_b32_e32 v104, 16, v148
	v_mad_i64_i32 v[64:65], s[16:17], v64, s90, v[144:145]
	v_cvt_pk_bf16_f32 v44, v44, v45
	v_cvt_pk_bf16_f32 v45, v46, v47
	v_cvt_pk_bf16_f32 v46, v40, v41
	v_add_u32_e32 v40, 0x90, v148
	v_lshl_add_u64 v[146:147], v[146:147], 0, v[142:143]
	v_cvt_pk_bf16_f32 v111, v106, v107
	v_mad_i64_i32 v[104:105], s[16:17], v104, s90, v[144:145]
	v_cvt_pk_bf16_f32 v92, v92, v93
	v_cvt_pk_bf16_f32 v93, v94, v95
	v_cvt_pk_bf16_f32 v94, v88, v89
	v_or_b32_e32 v88, 32, v148
	v_lshl_add_u64 v[64:65], v[64:65], 0, v[142:143]
	v_cvt_pk_bf16_f32 v47, v42, v43
	v_mad_i64_i32 v[40:41], s[16:17], v40, s90, v[144:145]
	v_cvt_pk_bf16_f32 v28, v28, v29
	v_cvt_pk_bf16_f32 v29, v30, v31
	v_cvt_pk_bf16_f32 v30, v24, v25
	v_add_u32_e32 v24, 0xa0, v148
	global_store_dwordx4 v[146:147], v[108:111], off offset:256 nt
	v_cvt_pk_bf16_f32 v95, v90, v91
	v_mad_i64_i32 v[88:89], s[16:17], v88, s90, v[144:145]
	v_lshl_add_u64 v[108:109], v[104:105], 0, v[142:143]
	v_cvt_pk_bf16_f32 v76, v76, v77
	v_cvt_pk_bf16_f32 v77, v78, v79
	v_cvt_pk_bf16_f32 v78, v72, v73
	v_or_b32_e32 v72, 48, v148
	global_store_dwordx4 v[64:65], v[44:47], off offset:256 nt
	v_cvt_pk_bf16_f32 v31, v26, v27
	v_mad_i64_i32 v[24:25], s[16:17], v24, s90, v[144:145]
	v_lshl_add_u64 v[44:45], v[40:41], 0, v[142:143]
	v_cvt_pk_bf16_f32 v12, v12, v13
	v_cvt_pk_bf16_f32 v13, v14, v15
	v_cvt_pk_bf16_f32 v14, v8, v9
	v_add_u32_e32 v8, 0xb0, v148
	global_store_dwordx4 v[108:109], v[92:95], off offset:256 nt
	v_cvt_pk_bf16_f32 v79, v74, v75
	v_mad_i64_i32 v[72:73], s[16:17], v72, s90, v[144:145]
	v_lshl_add_u64 v[92:93], v[88:89], 0, v[142:143]
	global_store_dwordx4 v[44:45], v[28:31], off offset:256 nt
	v_cvt_pk_bf16_f32 v15, v10, v11
	v_mad_i64_i32 v[8:9], s[16:17], v8, s90, v[144:145]
	v_lshl_add_u64 v[28:29], v[24:25], 0, v[142:143]
	v_cvt_pk_bf16_f32 v124, v124, v125
	v_cvt_pk_bf16_f32 v125, v126, v127
	v_cvt_pk_bf16_f32 v126, v120, v121
	v_cvt_pk_bf16_f32 v127, v122, v123
	v_cvt_pk_bf16_f32 v104, v116, v117
	v_cvt_pk_bf16_f32 v105, v118, v119
	v_cvt_pk_bf16_f32 v106, v112, v113
	v_cvt_pk_bf16_f32 v107, v114, v115
	v_cvt_pk_bf16_f32 v88, v100, v101
	v_cvt_pk_bf16_f32 v89, v102, v103
	v_cvt_pk_bf16_f32 v90, v96, v97
	v_cvt_pk_bf16_f32 v91, v98, v99
	global_store_dwordx4 v[92:93], v[76:79], off offset:256 nt
	v_cvt_pk_bf16_f32 v74, v80, v81
	v_cvt_pk_bf16_f32 v75, v82, v83
	v_lshl_add_u64 v[76:77], v[72:73], 0, v[142:143]
	v_cvt_pk_bf16_f32 v72, v84, v85
	v_cvt_pk_bf16_f32 v73, v86, v87
	v_cvt_pk_bf16_f32 v71, v66, v67
	v_cvt_pk_bf16_f32 v60, v60, v61
	v_cvt_pk_bf16_f32 v61, v62, v63
	v_cvt_pk_bf16_f32 v62, v56, v57
	v_cvt_pk_bf16_f32 v63, v58, v59
	v_cvt_pk_bf16_f32 v40, v52, v53
	v_cvt_pk_bf16_f32 v41, v54, v55
	v_cvt_pk_bf16_f32 v42, v48, v49
	v_cvt_pk_bf16_f32 v43, v50, v51
	v_cvt_pk_bf16_f32 v24, v36, v37
	v_cvt_pk_bf16_f32 v25, v38, v39
	v_cvt_pk_bf16_f32 v26, v32, v33
	v_cvt_pk_bf16_f32 v27, v34, v35
	global_store_dwordx4 v[28:29], v[12:15], off offset:256 nt
	v_cvt_pk_bf16_f32 v10, v16, v17
	v_cvt_pk_bf16_f32 v11, v18, v19
	v_lshl_add_u64 v[12:13], v[8:9], 0, v[142:143]
	v_cvt_pk_bf16_f32 v8, v20, v21
	v_cvt_pk_bf16_f32 v9, v22, v23
	v_cvt_pk_bf16_f32 v4, v4, v5
	v_cvt_pk_bf16_f32 v5, v6, v7
	v_cvt_pk_bf16_f32 v6, v0, v1
	v_cvt_pk_bf16_f32 v7, v2, v3
	s_andn2_b64 vcc, exec, s[0:1]
	s_mov_b64 s[0:1], -1
	s_movk_i32 s86, 0x4000
	s_movk_i32 s72, 0x2000
	s_mov_b32 s73, 0x14000
	global_store_dwordx4 v[146:147], v[124:127], off nt
	global_store_dwordx4 v[108:109], v[104:107], off nt
	global_store_dwordx4 v[92:93], v[88:91], off nt
	global_store_dwordx4 v[76:77], v[72:75], off nt
	global_store_dwordx4 v[76:77], v[68:71], off offset:256 nt
	global_store_dwordx4 v[64:65], v[60:63], off nt
	global_store_dwordx4 v[44:45], v[40:43], off nt
	global_store_dwordx4 v[28:29], v[24:27], off nt
	global_store_dwordx4 v[12:13], v[8:11], off nt
	global_store_dwordx4 v[12:13], v[4:7], off offset:256 nt
	s_cbranch_vccnz .LBB0_357
	s_andn2_b64 vcc, exec, s[4:5]
	s_cbranch_vccnz .LBB0_356
	s_barrier
	s_branch .LBB0_356

.LBB0_973:
	s_ashr_i32 s9, s55, 3
	v_lshl_add_u32 v152, s55, 8, v154
	v_lshl_or_b32 v48, s58, 8, v172
	s_mul_hi_i32 s11, s9, 0x9000
	s_mul_i32 s9, s9, 0x9000
	v_ashrrev_i32_e32 v153, 31, v152
	s_add_u32 s16, s50, s9
	v_ashrrev_i32_e32 v49, 31, v48
	v_lshlrev_b64 v[174:175], 12, v[152:153]
	s_addc_u32 s17, s51, s11
	v_lshlrev_b64 v[150:151], 2, v[48:49]
	v_lshl_add_u64 v[174:175], s[26:27], 0, v[174:175]
	v_lshl_add_u64 v[48:49], s[16:17], 0, v[150:151]
	v_lshl_add_u64 v[180:181], v[174:175], 0, v[150:151]
	global_load_dwordx4 v[104:107], v[48:49], off
	global_load_dwordx4 v[96:99], v[48:49], off offset:64
	global_load_dwordx4 v[84:87], v[48:49], off offset:512
	s_nop 0
	global_load_dwordx4 v[48:51], v[48:49], off offset:576
	s_mov_b64 s[16:17], -1
	global_load_dwordx4 v[174:177], v[180:181], off
	global_load_dwordx4 v[188:191], v[180:181], off offset:64
	global_load_dwordx4 v[192:195], v[180:181], off offset:512
	global_load_dwordx4 v[196:199], v[180:181], off offset:576
	s_andn2_b64 vcc, exec, s[0:1]
	s_waitcnt vmcnt(0)
	v_pk_fma_f32 v[142:143], v[142:143], v[106:107], v[176:177]
	v_pk_fma_f32 v[140:141], v[140:141], v[104:105], v[174:175]
	global_store_dwordx4 v[180:181], v[140:143], off nt
	v_pk_fma_f32 v[138:139], v[138:139], v[98:99], v[190:191]
	v_pk_fma_f32 v[136:137], v[136:137], v[96:97], v[188:189]
	global_store_dwordx4 v[180:181], v[136:139], off offset:64 nt
	v_pk_fma_f32 v[134:135], v[134:135], v[86:87], v[194:195]
	v_pk_fma_f32 v[132:133], v[132:133], v[84:85], v[192:193]
	global_store_dwordx4 v[180:181], v[132:135], off offset:512 nt
	v_pk_fma_f32 v[130:131], v[130:131], v[50:51], v[198:199]
	v_pk_fma_f32 v[128:129], v[128:129], v[48:49], v[196:197]
	global_store_dwordx4 v[180:181], v[128:131], off offset:576 nt
	s_nop 1
	v_or_b32_e32 v128, 16, v152
	v_ashrrev_i32_e32 v129, 31, v128
	v_lshlrev_b64 v[128:129], 12, v[128:129]
	v_lshl_add_u64 v[128:129], s[26:27], 0, v[128:129]
	v_lshl_add_u64 v[132:133], v[128:129], 0, v[150:151]
	global_load_dwordx4 v[128:131], v[132:133], off
	global_load_dwordx4 v[188:191], v[132:133], off offset:64
	global_load_dwordx4 v[192:195], v[132:133], off offset:512
	global_load_dwordx4 v[196:199], v[132:133], off offset:576
	s_waitcnt vmcnt(0)
	v_pk_fma_f32 v[126:127], v[126:127], v[106:107], v[130:131]
	v_pk_fma_f32 v[124:125], v[124:125], v[104:105], v[128:129]
	global_store_dwordx4 v[132:133], v[124:127], off nt
	v_pk_fma_f32 v[122:123], v[122:123], v[98:99], v[190:191]
	v_pk_fma_f32 v[120:121], v[120:121], v[96:97], v[188:189]
	global_store_dwordx4 v[132:133], v[120:123], off offset:64 nt
	v_pk_fma_f32 v[118:119], v[118:119], v[86:87], v[194:195]
	v_pk_fma_f32 v[116:117], v[116:117], v[84:85], v[192:193]
	global_store_dwordx4 v[132:133], v[116:119], off offset:512 nt
	v_pk_fma_f32 v[114:115], v[114:115], v[50:51], v[198:199]
	v_pk_fma_f32 v[112:113], v[112:113], v[48:49], v[196:197]
	global_store_dwordx4 v[132:133], v[112:115], off offset:576 nt
	s_nop 1
	v_or_b32_e32 v112, 32, v152
	v_ashrrev_i32_e32 v113, 31, v112
	v_lshlrev_b64 v[112:113], 12, v[112:113]
	v_lshl_add_u64 v[112:113], s[26:27], 0, v[112:113]
	v_lshl_add_u64 v[116:117], v[112:113], 0, v[150:151]
	global_load_dwordx4 v[112:115], v[116:117], off
	global_load_dwordx4 v[188:191], v[116:117], off offset:64
	global_load_dwordx4 v[192:195], v[116:117], off offset:512
	global_load_dwordx4 v[196:199], v[116:117], off offset:576
	s_waitcnt vmcnt(0)
	v_pk_fma_f32 v[110:111], v[110:111], v[106:107], v[114:115]
	v_pk_fma_f32 v[108:109], v[108:109], v[104:105], v[112:113]
	global_store_dwordx4 v[116:117], v[108:111], off nt
	v_pk_fma_f32 v[102:103], v[102:103], v[98:99], v[190:191]
	v_pk_fma_f32 v[100:101], v[100:101], v[96:97], v[188:189]
	global_store_dwordx4 v[116:117], v[100:103], off offset:64 nt
	v_pk_fma_f32 v[94:95], v[94:95], v[86:87], v[194:195]
	v_pk_fma_f32 v[92:93], v[92:93], v[84:85], v[192:193]
	global_store_dwordx4 v[116:117], v[92:95], off offset:512 nt
	v_pk_fma_f32 v[90:91], v[90:91], v[50:51], v[198:199]
	v_pk_fma_f32 v[88:89], v[88:89], v[48:49], v[196:197]
	global_store_dwordx4 v[116:117], v[88:91], off offset:576 nt
	s_nop 1
	v_or_b32_e32 v88, 48, v152
	v_ashrrev_i32_e32 v89, 31, v88
	v_lshlrev_b64 v[88:89], 12, v[88:89]
	v_lshl_add_u64 v[88:89], s[26:27], 0, v[88:89]
	v_lshl_add_u64 v[92:93], v[88:89], 0, v[150:151]
	global_load_dwordx4 v[88:91], v[92:93], off
	global_load_dwordx4 v[188:191], v[92:93], off offset:64
	global_load_dwordx4 v[192:195], v[92:93], off offset:512
	global_load_dwordx4 v[196:199], v[92:93], off offset:576
	s_waitcnt vmcnt(0)
	v_pk_fma_f32 v[82:83], v[82:83], v[106:107], v[90:91]
	v_pk_fma_f32 v[80:81], v[80:81], v[104:105], v[88:89]
	global_store_dwordx4 v[92:93], v[80:83], off nt
	v_pk_fma_f32 v[78:79], v[78:79], v[98:99], v[190:191]
	v_pk_fma_f32 v[76:77], v[76:77], v[96:97], v[188:189]
	global_store_dwordx4 v[92:93], v[76:79], off offset:64 nt
	v_pk_fma_f32 v[74:75], v[74:75], v[86:87], v[194:195]
	v_pk_fma_f32 v[72:73], v[72:73], v[84:85], v[192:193]
	global_store_dwordx4 v[92:93], v[72:75], off offset:512 nt
	v_pk_fma_f32 v[70:71], v[70:71], v[50:51], v[198:199]
	v_pk_fma_f32 v[68:69], v[68:69], v[48:49], v[196:197]
	global_store_dwordx4 v[92:93], v[68:71], off offset:576 nt
	s_nop 1
	v_add_u32_e32 v68, 0x80, v152
	v_ashrrev_i32_e32 v69, 31, v68
	v_lshlrev_b64 v[68:69], 12, v[68:69]
	v_lshl_add_u64 v[68:69], s[26:27], 0, v[68:69]
	v_lshl_add_u64 v[72:73], v[68:69], 0, v[150:151]
	global_load_dwordx4 v[68:71], v[72:73], off
	global_load_dwordx4 v[188:191], v[72:73], off offset:64
	global_load_dwordx4 v[192:195], v[72:73], off offset:512
	global_load_dwordx4 v[196:199], v[72:73], off offset:576
	s_waitcnt vmcnt(0)
	v_pk_fma_f32 v[66:67], v[66:67], v[106:107], v[70:71]
	v_pk_fma_f32 v[64:65], v[64:65], v[104:105], v[68:69]
	global_store_dwordx4 v[72:73], v[64:67], off nt
	v_pk_fma_f32 v[62:63], v[62:63], v[98:99], v[190:191]
	v_pk_fma_f32 v[60:61], v[60:61], v[96:97], v[188:189]
	global_store_dwordx4 v[72:73], v[60:63], off offset:64 nt
	v_pk_fma_f32 v[58:59], v[58:59], v[86:87], v[194:195]
	v_pk_fma_f32 v[56:57], v[56:57], v[84:85], v[192:193]
	global_store_dwordx4 v[72:73], v[56:59], off offset:512 nt
	v_pk_fma_f32 v[54:55], v[54:55], v[50:51], v[198:199]
	v_pk_fma_f32 v[52:53], v[52:53], v[48:49], v[196:197]
	global_store_dwordx4 v[72:73], v[52:55], off offset:576 nt
	s_nop 1
	v_add_u32_e32 v52, 0x90, v152
	v_ashrrev_i32_e32 v53, 31, v52
	v_lshlrev_b64 v[52:53], 12, v[52:53]
	v_lshl_add_u64 v[52:53], s[26:27], 0, v[52:53]
	v_lshl_add_u64 v[56:57], v[52:53], 0, v[150:151]
	global_load_dwordx4 v[52:55], v[56:57], off
	global_load_dwordx4 v[188:191], v[56:57], off offset:64
	global_load_dwordx4 v[192:195], v[56:57], off offset:512
	global_load_dwordx4 v[196:199], v[56:57], off offset:576
	s_waitcnt vmcnt(0)
	v_pk_fma_f32 v[46:47], v[46:47], v[106:107], v[54:55]
	v_pk_fma_f32 v[44:45], v[44:45], v[104:105], v[52:53]
	global_store_dwordx4 v[56:57], v[44:47], off nt
	v_pk_fma_f32 v[42:43], v[42:43], v[98:99], v[190:191]
	v_pk_fma_f32 v[40:41], v[40:41], v[96:97], v[188:189]
	global_store_dwordx4 v[56:57], v[40:43], off offset:64 nt
	v_pk_fma_f32 v[38:39], v[38:39], v[86:87], v[194:195]
	v_pk_fma_f32 v[36:37], v[36:37], v[84:85], v[192:193]
	global_store_dwordx4 v[56:57], v[36:39], off offset:512 nt
	v_pk_fma_f32 v[34:35], v[34:35], v[50:51], v[198:199]
	v_pk_fma_f32 v[32:33], v[32:33], v[48:49], v[196:197]
	global_store_dwordx4 v[56:57], v[32:35], off offset:576 nt
	s_nop 1
	v_add_u32_e32 v32, 0xa0, v152
	v_ashrrev_i32_e32 v33, 31, v32
	v_lshlrev_b64 v[32:33], 12, v[32:33]
	v_lshl_add_u64 v[32:33], s[26:27], 0, v[32:33]
	v_lshl_add_u64 v[36:37], v[32:33], 0, v[150:151]
	global_load_dwordx4 v[32:35], v[36:37], off
	global_load_dwordx4 v[188:191], v[36:37], off offset:64
	global_load_dwordx4 v[192:195], v[36:37], off offset:512
	global_load_dwordx4 v[196:199], v[36:37], off offset:576
	s_waitcnt vmcnt(0)
	v_pk_fma_f32 v[30:31], v[30:31], v[106:107], v[34:35]
	v_pk_fma_f32 v[28:29], v[28:29], v[104:105], v[32:33]
	global_store_dwordx4 v[36:37], v[28:31], off nt
	v_pk_fma_f32 v[26:27], v[26:27], v[98:99], v[190:191]
	v_pk_fma_f32 v[24:25], v[24:25], v[96:97], v[188:189]
	global_store_dwordx4 v[36:37], v[24:27], off offset:64 nt
	v_pk_fma_f32 v[22:23], v[22:23], v[86:87], v[194:195]
	v_pk_fma_f32 v[20:21], v[20:21], v[84:85], v[192:193]
	global_store_dwordx4 v[36:37], v[20:23], off offset:512 nt
	v_pk_fma_f32 v[18:19], v[18:19], v[50:51], v[198:199]
	v_pk_fma_f32 v[16:17], v[16:17], v[48:49], v[196:197]
	global_store_dwordx4 v[36:37], v[16:19], off offset:576 nt
	s_nop 1
	v_add_u32_e32 v16, 0xb0, v152
	v_ashrrev_i32_e32 v17, 31, v16
	v_lshlrev_b64 v[16:17], 12, v[16:17]
	v_lshl_add_u64 v[16:17], s[26:27], 0, v[16:17]
	v_lshl_add_u64 v[16:17], v[16:17], 0, v[150:151]
	global_load_dwordx4 v[18:21], v[16:17], off
	global_load_dwordx4 v[188:191], v[16:17], off offset:64
	global_load_dwordx4 v[192:195], v[16:17], off offset:512
	global_load_dwordx4 v[196:199], v[16:17], off offset:576
	s_waitcnt vmcnt(0)
	v_pk_fma_f32 v[14:15], v[14:15], v[106:107], v[20:21]
	v_pk_fma_f32 v[12:13], v[12:13], v[104:105], v[18:19]
	global_store_dwordx4 v[16:17], v[12:15], off nt
	v_pk_fma_f32 v[10:11], v[10:11], v[98:99], v[190:191]
	v_pk_fma_f32 v[8:9], v[8:9], v[96:97], v[188:189]
	global_store_dwordx4 v[16:17], v[8:11], off offset:64 nt
	v_pk_fma_f32 v[6:7], v[6:7], v[86:87], v[194:195]
	v_pk_fma_f32 v[4:5], v[4:5], v[84:85], v[192:193]
	global_store_dwordx4 v[16:17], v[4:7], off offset:512 nt
	v_pk_fma_f32 v[2:3], v[2:3], v[50:51], v[198:199]
	v_pk_fma_f32 v[0:1], v[0:1], v[48:49], v[196:197]
	global_store_dwordx4 v[16:17], v[0:3], off offset:576 nt
	s_cbranch_vccnz .LBB0_962
	s_andn2_b64 vcc, exec, s[4:5]
	s_cbranch_vccnz .LBB0_961
	s_barrier
	s_branch .LBB0_961

.LBB0_1099:
	v_mul_f32_e32 v147, 0xbfb8aa3b, v124
	v_exp_f32_e32 v147, v147
	v_lshl_add_u32 v146, s52, 8, v142
	v_lshl_or_b32 v140, s51, 7, v144
	v_ashrrev_i32_e32 v141, 31, v140
	v_add_f32_e32 v147, 1.0, v147
	v_rcp_f32_e32 v150, v147
	v_mul_f32_e32 v147, 0xbfb8aa3b, v125
	v_exp_f32_e32 v147, v147
	v_mov_b64_e32 v[138:139], s[20:21]
	v_mad_i64_i32 v[148:149], s[16:17], v146, s82, v[138:139]
	v_add_f32_e32 v147, 1.0, v147
	v_rcp_f32_e32 v151, v147
	v_lshlrev_b64 v[140:141], 1, v[140:141]
	v_lshl_add_u64 v[148:149], v[148:149], 0, v[140:141]
	s_andn2_b64 vcc, exec, s[0:1]
	v_pk_mul_f32 v[124:125], v[124:125], v[150:151]
	s_movk_i32 s86, 0x4000
	v_pk_mul_f32 v[120:121], v[124:125], v[120:121]
	s_movk_i32 s72, 0x2000
	v_cvt_pk_bf16_f32 v120, v120, v121
	v_mul_f32_e32 v121, 0xbfb8aa3b, v126
	v_exp_f32_e32 v121, v121
	s_mov_b32 s73, 0x14000
	v_add_f32_e32 v121, 1.0, v121
	v_rcp_f32_e32 v124, v121
	v_mul_f32_e32 v121, 0xbfb8aa3b, v127
	v_exp_f32_e32 v121, v121
	s_nop 0
	v_add_f32_e32 v121, 1.0, v121
	v_rcp_f32_e32 v125, v121
	s_nop 0
	v_pk_mul_f32 v[124:125], v[126:127], v[124:125]
	s_nop 0
	v_pk_mul_f32 v[122:123], v[124:125], v[122:123]
	s_nop 0
	v_cvt_pk_bf16_f32 v121, v122, v123
	v_mul_f32_e32 v122, 0xbfb8aa3b, v116
	v_mul_f32_e32 v123, 0xbfb8aa3b, v117
	v_exp_f32_e32 v122, v122
	v_exp_f32_e32 v123, v123
	v_add_f32_e32 v122, 1.0, v122
	v_add_f32_e32 v123, 1.0, v123
	v_rcp_f32_e32 v122, v122
	v_rcp_f32_e32 v123, v123
	s_nop 0
	v_pk_mul_f32 v[116:117], v[116:117], v[122:123]
	s_nop 0
	v_pk_mul_f32 v[112:113], v[116:117], v[112:113]
	s_nop 0
	v_cvt_pk_bf16_f32 v122, v112, v113
	v_mul_f32_e32 v112, 0xbfb8aa3b, v118
	v_mul_f32_e32 v113, 0xbfb8aa3b, v119
	v_exp_f32_e32 v112, v112
	v_exp_f32_e32 v113, v113
	v_add_f32_e32 v112, 1.0, v112
	v_add_f32_e32 v113, 1.0, v113
	v_rcp_f32_e32 v112, v112
	v_rcp_f32_e32 v113, v113
	s_nop 0
	v_pk_mul_f32 v[112:113], v[118:119], v[112:113]
	s_nop 0
	v_pk_mul_f32 v[112:113], v[112:113], v[114:115]
	v_mul_f32_e32 v114, 0xbfb8aa3b, v108
	v_mul_f32_e32 v115, 0xbfb8aa3b, v109
	v_exp_f32_e32 v114, v114
	v_exp_f32_e32 v115, v115
	v_cvt_pk_bf16_f32 v123, v112, v113
	v_or_b32_e32 v112, 16, v146
	v_add_f32_e32 v114, 1.0, v114
	v_add_f32_e32 v115, 1.0, v115
	v_rcp_f32_e32 v114, v114
	v_rcp_f32_e32 v115, v115
	v_mad_i64_i32 v[112:113], s[16:17], v112, s82, v[138:139]
	v_lshl_add_u64 v[112:113], v[112:113], 0, v[140:141]
	v_pk_mul_f32 v[108:109], v[108:109], v[114:115]
	global_store_dwordx4 v[148:149], v[120:123], off nt
	v_pk_mul_f32 v[104:105], v[108:109], v[104:105]
	s_nop 0
	v_cvt_pk_bf16_f32 v104, v104, v105
	v_mul_f32_e32 v105, 0xbfb8aa3b, v110
	v_exp_f32_e32 v105, v105
	s_nop 0
	v_add_f32_e32 v105, 1.0, v105
	v_rcp_f32_e32 v108, v105
	v_mul_f32_e32 v105, 0xbfb8aa3b, v111
	v_exp_f32_e32 v105, v105
	s_nop 0
	v_add_f32_e32 v105, 1.0, v105
	v_rcp_f32_e32 v109, v105
	s_nop 0
	v_pk_mul_f32 v[108:109], v[110:111], v[108:109]
	s_nop 0
	v_pk_mul_f32 v[106:107], v[108:109], v[106:107]
	s_nop 0
	v_cvt_pk_bf16_f32 v105, v106, v107
	v_mul_f32_e32 v106, 0xbfb8aa3b, v100
	v_mul_f32_e32 v107, 0xbfb8aa3b, v101
	v_exp_f32_e32 v106, v106
	v_exp_f32_e32 v107, v107
	v_add_f32_e32 v106, 1.0, v106
	v_add_f32_e32 v107, 1.0, v107
	v_rcp_f32_e32 v106, v106
	v_rcp_f32_e32 v107, v107
	s_nop 0
	v_pk_mul_f32 v[100:101], v[100:101], v[106:107]
	s_nop 0
	v_pk_mul_f32 v[96:97], v[100:101], v[96:97]
	s_nop 0
	v_cvt_pk_bf16_f32 v106, v96, v97
	v_mul_f32_e32 v96, 0xbfb8aa3b, v102
	v_mul_f32_e32 v97, 0xbfb8aa3b, v103
	v_exp_f32_e32 v96, v96
	v_exp_f32_e32 v97, v97
	v_add_f32_e32 v96, 1.0, v96
	v_add_f32_e32 v97, 1.0, v97
	v_rcp_f32_e32 v96, v96
	v_rcp_f32_e32 v97, v97
	s_nop 0
	v_pk_mul_f32 v[96:97], v[102:103], v[96:97]
	s_nop 0
	v_pk_mul_f32 v[96:97], v[96:97], v[98:99]
	v_mul_f32_e32 v98, 0xbfb8aa3b, v92
	v_mul_f32_e32 v99, 0xbfb8aa3b, v93
	v_exp_f32_e32 v98, v98
	v_exp_f32_e32 v99, v99
	v_cvt_pk_bf16_f32 v107, v96, v97
	v_or_b32_e32 v96, 32, v146
	v_add_f32_e32 v98, 1.0, v98
	v_add_f32_e32 v99, 1.0, v99
	v_rcp_f32_e32 v98, v98
	v_rcp_f32_e32 v99, v99
	v_mad_i64_i32 v[96:97], s[16:17], v96, s82, v[138:139]
	v_lshl_add_u64 v[96:97], v[96:97], 0, v[140:141]
	v_pk_mul_f32 v[92:93], v[92:93], v[98:99]
	global_store_dwordx4 v[112:113], v[104:107], off nt
	v_pk_mul_f32 v[88:89], v[92:93], v[88:89]
	s_nop 0
	v_cvt_pk_bf16_f32 v88, v88, v89
	v_mul_f32_e32 v89, 0xbfb8aa3b, v94
	v_exp_f32_e32 v89, v89
	s_nop 0
	v_add_f32_e32 v89, 1.0, v89
	v_rcp_f32_e32 v92, v89
	v_mul_f32_e32 v89, 0xbfb8aa3b, v95
	v_exp_f32_e32 v89, v89
	s_nop 0
	v_add_f32_e32 v89, 1.0, v89
	v_rcp_f32_e32 v93, v89
	s_nop 0
	v_pk_mul_f32 v[92:93], v[94:95], v[92:93]
	s_nop 0
	v_pk_mul_f32 v[90:91], v[92:93], v[90:91]
	s_nop 0
	v_cvt_pk_bf16_f32 v89, v90, v91
	v_mul_f32_e32 v90, 0xbfb8aa3b, v84
	v_mul_f32_e32 v91, 0xbfb8aa3b, v85
	v_exp_f32_e32 v90, v90
	v_exp_f32_e32 v91, v91
	v_add_f32_e32 v90, 1.0, v90
	v_add_f32_e32 v91, 1.0, v91
	v_rcp_f32_e32 v90, v90
	v_rcp_f32_e32 v91, v91
	s_nop 0
	v_pk_mul_f32 v[84:85], v[84:85], v[90:91]
	s_nop 0
	v_pk_mul_f32 v[80:81], v[84:85], v[80:81]
	s_nop 0
	v_cvt_pk_bf16_f32 v90, v80, v81
	v_mul_f32_e32 v80, 0xbfb8aa3b, v86
	v_mul_f32_e32 v81, 0xbfb8aa3b, v87
	v_exp_f32_e32 v80, v80
	v_exp_f32_e32 v81, v81
	v_add_f32_e32 v80, 1.0, v80
	v_add_f32_e32 v81, 1.0, v81
	v_rcp_f32_e32 v80, v80
	v_rcp_f32_e32 v81, v81
	s_nop 0
	v_pk_mul_f32 v[80:81], v[86:87], v[80:81]
	s_nop 0
	v_pk_mul_f32 v[80:81], v[80:81], v[82:83]
	v_mul_f32_e32 v82, 0xbfb8aa3b, v76
	v_mul_f32_e32 v83, 0xbfb8aa3b, v77
	v_exp_f32_e32 v82, v82
	v_exp_f32_e32 v83, v83
	v_cvt_pk_bf16_f32 v91, v80, v81
	v_or_b32_e32 v80, 48, v146
	v_add_f32_e32 v82, 1.0, v82
	v_add_f32_e32 v83, 1.0, v83
	v_rcp_f32_e32 v82, v82
	v_rcp_f32_e32 v83, v83
	v_mad_i64_i32 v[80:81], s[16:17], v80, s82, v[138:139]
	v_lshl_add_u64 v[80:81], v[80:81], 0, v[140:141]
	v_pk_mul_f32 v[76:77], v[76:77], v[82:83]
	global_store_dwordx4 v[96:97], v[88:91], off nt
	v_pk_mul_f32 v[72:73], v[76:77], v[72:73]
	s_nop 0
	v_cvt_pk_bf16_f32 v72, v72, v73
	v_mul_f32_e32 v73, 0xbfb8aa3b, v78
	v_exp_f32_e32 v73, v73
	s_nop 0
	v_add_f32_e32 v73, 1.0, v73
	v_rcp_f32_e32 v76, v73
	v_mul_f32_e32 v73, 0xbfb8aa3b, v79
	v_exp_f32_e32 v73, v73
	s_nop 0
	v_add_f32_e32 v73, 1.0, v73
	v_rcp_f32_e32 v77, v73
	s_nop 0
	v_pk_mul_f32 v[76:77], v[78:79], v[76:77]
	s_nop 0
	v_pk_mul_f32 v[74:75], v[76:77], v[74:75]
	s_nop 0
	v_cvt_pk_bf16_f32 v73, v74, v75
	v_mul_f32_e32 v74, 0xbfb8aa3b, v68
	v_mul_f32_e32 v75, 0xbfb8aa3b, v69
	v_exp_f32_e32 v74, v74
	v_exp_f32_e32 v75, v75
	v_add_f32_e32 v74, 1.0, v74
	v_add_f32_e32 v75, 1.0, v75
	v_rcp_f32_e32 v74, v74
	v_rcp_f32_e32 v75, v75
	s_nop 0
	v_pk_mul_f32 v[68:69], v[68:69], v[74:75]
	s_nop 0
	v_pk_mul_f32 v[64:65], v[68:69], v[64:65]
	s_nop 0
	v_cvt_pk_bf16_f32 v74, v64, v65
	v_mul_f32_e32 v64, 0xbfb8aa3b, v70
	v_mul_f32_e32 v65, 0xbfb8aa3b, v71
	v_exp_f32_e32 v64, v64
	v_exp_f32_e32 v65, v65
	v_add_f32_e32 v64, 1.0, v64
	v_add_f32_e32 v65, 1.0, v65
	v_rcp_f32_e32 v64, v64
	v_rcp_f32_e32 v65, v65
	s_nop 0
	v_pk_mul_f32 v[64:65], v[70:71], v[64:65]
	s_nop 0
	v_pk_mul_f32 v[64:65], v[64:65], v[66:67]
	v_mul_f32_e32 v66, 0xbfb8aa3b, v60
	v_mul_f32_e32 v67, 0xbfb8aa3b, v61
	v_exp_f32_e32 v66, v66
	v_exp_f32_e32 v67, v67
	v_cvt_pk_bf16_f32 v75, v64, v65
	v_add_u32_e32 v64, 0x80, v146
	v_add_f32_e32 v66, 1.0, v66
	v_add_f32_e32 v67, 1.0, v67
	v_rcp_f32_e32 v66, v66
	v_rcp_f32_e32 v67, v67
	v_mad_i64_i32 v[64:65], s[16:17], v64, s82, v[138:139]
	v_lshl_add_u64 v[64:65], v[64:65], 0, v[140:141]
	v_pk_mul_f32 v[60:61], v[60:61], v[66:67]
	global_store_dwordx4 v[80:81], v[72:75], off nt
	v_pk_mul_f32 v[56:57], v[60:61], v[56:57]
	s_nop 0
	v_cvt_pk_bf16_f32 v56, v56, v57
	v_mul_f32_e32 v57, 0xbfb8aa3b, v62
	v_exp_f32_e32 v57, v57
	s_nop 0
	v_add_f32_e32 v57, 1.0, v57
	v_rcp_f32_e32 v60, v57
	v_mul_f32_e32 v57, 0xbfb8aa3b, v63
	v_exp_f32_e32 v57, v57
	s_nop 0
	v_add_f32_e32 v57, 1.0, v57
	v_rcp_f32_e32 v61, v57
	s_nop 0
	v_pk_mul_f32 v[60:61], v[62:63], v[60:61]
	s_nop 0
	v_pk_mul_f32 v[58:59], v[60:61], v[58:59]
	s_nop 0
	v_cvt_pk_bf16_f32 v57, v58, v59
	v_mul_f32_e32 v58, 0xbfb8aa3b, v52
	v_mul_f32_e32 v59, 0xbfb8aa3b, v53
	v_exp_f32_e32 v58, v58
	v_exp_f32_e32 v59, v59
	v_add_f32_e32 v58, 1.0, v58
	v_add_f32_e32 v59, 1.0, v59
	v_rcp_f32_e32 v58, v58
	v_rcp_f32_e32 v59, v59
	s_nop 0
	v_pk_mul_f32 v[52:53], v[52:53], v[58:59]
	s_nop 0
	v_pk_mul_f32 v[48:49], v[52:53], v[48:49]
	s_nop 0
	v_cvt_pk_bf16_f32 v58, v48, v49
	v_mul_f32_e32 v48, 0xbfb8aa3b, v54
	v_mul_f32_e32 v49, 0xbfb8aa3b, v55
	v_exp_f32_e32 v48, v48
	v_exp_f32_e32 v49, v49
	v_add_f32_e32 v48, 1.0, v48
	v_add_f32_e32 v49, 1.0, v49
	v_rcp_f32_e32 v48, v48
	v_rcp_f32_e32 v49, v49
	s_nop 0
	v_pk_mul_f32 v[48:49], v[54:55], v[48:49]
	s_nop 0
	v_pk_mul_f32 v[48:49], v[48:49], v[50:51]
	v_mul_f32_e32 v50, 0xbfb8aa3b, v44
	v_mul_f32_e32 v51, 0xbfb8aa3b, v45
	v_exp_f32_e32 v50, v50
	v_exp_f32_e32 v51, v51
	v_cvt_pk_bf16_f32 v59, v48, v49
	v_add_u32_e32 v48, 0x90, v146
	v_add_f32_e32 v50, 1.0, v50
	v_add_f32_e32 v51, 1.0, v51
	v_rcp_f32_e32 v50, v50
	v_rcp_f32_e32 v51, v51
	v_mad_i64_i32 v[48:49], s[16:17], v48, s82, v[138:139]
	v_lshl_add_u64 v[48:49], v[48:49], 0, v[140:141]
	v_pk_mul_f32 v[44:45], v[44:45], v[50:51]
	global_store_dwordx4 v[64:65], v[56:59], off nt
	v_pk_mul_f32 v[40:41], v[44:45], v[40:41]
	s_nop 0
	v_cvt_pk_bf16_f32 v40, v40, v41
	v_mul_f32_e32 v41, 0xbfb8aa3b, v46
	v_exp_f32_e32 v41, v41
	s_nop 0
	v_add_f32_e32 v41, 1.0, v41
	v_rcp_f32_e32 v44, v41
	v_mul_f32_e32 v41, 0xbfb8aa3b, v47
	v_exp_f32_e32 v41, v41
	s_nop 0
	v_add_f32_e32 v41, 1.0, v41
	v_rcp_f32_e32 v45, v41
	s_nop 0
	v_pk_mul_f32 v[44:45], v[46:47], v[44:45]
	s_nop 0
	v_pk_mul_f32 v[42:43], v[44:45], v[42:43]
	s_nop 0
	v_cvt_pk_bf16_f32 v41, v42, v43
	v_mul_f32_e32 v42, 0xbfb8aa3b, v36
	v_mul_f32_e32 v43, 0xbfb8aa3b, v37
	v_exp_f32_e32 v42, v42
	v_exp_f32_e32 v43, v43
	v_add_f32_e32 v42, 1.0, v42
	v_add_f32_e32 v43, 1.0, v43
	v_rcp_f32_e32 v42, v42
	v_rcp_f32_e32 v43, v43
	s_nop 0
	v_pk_mul_f32 v[36:37], v[36:37], v[42:43]
	s_nop 0
	v_pk_mul_f32 v[32:33], v[36:37], v[32:33]
	s_nop 0
	v_cvt_pk_bf16_f32 v42, v32, v33
	v_mul_f32_e32 v32, 0xbfb8aa3b, v38
	v_mul_f32_e32 v33, 0xbfb8aa3b, v39
	v_exp_f32_e32 v32, v32
	v_exp_f32_e32 v33, v33
	v_add_f32_e32 v32, 1.0, v32
	v_add_f32_e32 v33, 1.0, v33
	v_rcp_f32_e32 v32, v32
	v_rcp_f32_e32 v33, v33
	s_nop 0
	v_pk_mul_f32 v[32:33], v[38:39], v[32:33]
	s_nop 0
	v_pk_mul_f32 v[32:33], v[32:33], v[34:35]
	v_mul_f32_e32 v34, 0xbfb8aa3b, v28
	v_mul_f32_e32 v35, 0xbfb8aa3b, v29
	v_exp_f32_e32 v34, v34
	v_exp_f32_e32 v35, v35
	v_cvt_pk_bf16_f32 v43, v32, v33
	v_add_u32_e32 v32, 0xa0, v146
	v_add_f32_e32 v34, 1.0, v34
	v_add_f32_e32 v35, 1.0, v35
	v_rcp_f32_e32 v34, v34
	v_rcp_f32_e32 v35, v35
	v_mad_i64_i32 v[32:33], s[16:17], v32, s82, v[138:139]
	v_lshl_add_u64 v[32:33], v[32:33], 0, v[140:141]
	v_pk_mul_f32 v[28:29], v[28:29], v[34:35]
	global_store_dwordx4 v[48:49], v[40:43], off nt
	v_pk_mul_f32 v[24:25], v[28:29], v[24:25]
	s_nop 0
	v_cvt_pk_bf16_f32 v24, v24, v25
	v_mul_f32_e32 v25, 0xbfb8aa3b, v30
	v_exp_f32_e32 v25, v25
	s_nop 0
	v_add_f32_e32 v25, 1.0, v25
	v_rcp_f32_e32 v28, v25
	v_mul_f32_e32 v25, 0xbfb8aa3b, v31
	v_exp_f32_e32 v25, v25
	s_nop 0
	v_add_f32_e32 v25, 1.0, v25
	v_rcp_f32_e32 v29, v25
	s_nop 0
	v_pk_mul_f32 v[28:29], v[30:31], v[28:29]
	s_nop 0
	v_pk_mul_f32 v[26:27], v[28:29], v[26:27]
	s_nop 0
	v_cvt_pk_bf16_f32 v25, v26, v27
	v_mul_f32_e32 v26, 0xbfb8aa3b, v20
	v_mul_f32_e32 v27, 0xbfb8aa3b, v21
	v_exp_f32_e32 v26, v26
	v_exp_f32_e32 v27, v27
	v_add_f32_e32 v26, 1.0, v26
	v_add_f32_e32 v27, 1.0, v27
	v_rcp_f32_e32 v26, v26
	v_rcp_f32_e32 v27, v27
	s_nop 0
	v_pk_mul_f32 v[20:21], v[20:21], v[26:27]
	s_nop 0
	v_pk_mul_f32 v[16:17], v[20:21], v[16:17]
	s_nop 0
	v_cvt_pk_bf16_f32 v26, v16, v17
	v_mul_f32_e32 v16, 0xbfb8aa3b, v22
	v_mul_f32_e32 v17, 0xbfb8aa3b, v23
	v_exp_f32_e32 v16, v16
	v_exp_f32_e32 v17, v17
	v_add_f32_e32 v16, 1.0, v16
	v_add_f32_e32 v17, 1.0, v17
	v_rcp_f32_e32 v16, v16
	v_rcp_f32_e32 v17, v17
	s_nop 0
	v_pk_mul_f32 v[16:17], v[22:23], v[16:17]
	s_nop 0
	v_pk_mul_f32 v[16:17], v[16:17], v[18:19]
	v_mul_f32_e32 v18, 0xbfb8aa3b, v12
	v_mul_f32_e32 v19, 0xbfb8aa3b, v13
	v_exp_f32_e32 v18, v18
	v_exp_f32_e32 v19, v19
	v_cvt_pk_bf16_f32 v27, v16, v17
	v_add_u32_e32 v16, 0xb0, v146
	v_add_f32_e32 v18, 1.0, v18
	v_add_f32_e32 v19, 1.0, v19
	v_rcp_f32_e32 v18, v18
	v_rcp_f32_e32 v19, v19
	v_mad_i64_i32 v[16:17], s[16:17], v16, s82, v[138:139]
	v_lshl_add_u64 v[16:17], v[16:17], 0, v[140:141]
	v_pk_mul_f32 v[12:13], v[12:13], v[18:19]
	s_mov_b64 s[16:17], -1
	v_pk_mul_f32 v[8:9], v[12:13], v[8:9]
	global_store_dwordx4 v[32:33], v[24:27], off nt
	v_cvt_pk_bf16_f32 v8, v8, v9
	v_mul_f32_e32 v9, 0xbfb8aa3b, v14
	v_exp_f32_e32 v9, v9
	s_nop 0
	v_add_f32_e32 v9, 1.0, v9
	v_rcp_f32_e32 v12, v9
	v_mul_f32_e32 v9, 0xbfb8aa3b, v15
	v_exp_f32_e32 v9, v9
	s_nop 0
	v_add_f32_e32 v9, 1.0, v9
	v_rcp_f32_e32 v13, v9
	s_nop 0
	v_pk_mul_f32 v[12:13], v[14:15], v[12:13]
	s_nop 0
	v_pk_mul_f32 v[10:11], v[12:13], v[10:11]
	s_nop 0
	v_cvt_pk_bf16_f32 v9, v10, v11
	v_mul_f32_e32 v10, 0xbfb8aa3b, v4
	v_mul_f32_e32 v11, 0xbfb8aa3b, v5
	v_exp_f32_e32 v10, v10
	v_exp_f32_e32 v11, v11
	v_add_f32_e32 v10, 1.0, v10
	v_add_f32_e32 v11, 1.0, v11
	v_rcp_f32_e32 v10, v10
	v_rcp_f32_e32 v11, v11
	s_nop 0
	v_pk_mul_f32 v[4:5], v[4:5], v[10:11]
	s_nop 0
	v_pk_mul_f32 v[0:1], v[4:5], v[0:1]
	s_nop 0
	v_cvt_pk_bf16_f32 v10, v0, v1
	v_mul_f32_e32 v0, 0xbfb8aa3b, v6
	v_mul_f32_e32 v1, 0xbfb8aa3b, v7
	v_exp_f32_e32 v0, v0
	v_exp_f32_e32 v1, v1
	v_add_f32_e32 v0, 1.0, v0
	v_add_f32_e32 v1, 1.0, v1
	v_rcp_f32_e32 v0, v0
	v_rcp_f32_e32 v1, v1
	s_nop 0
	v_pk_mul_f32 v[0:1], v[6:7], v[0:1]
	s_nop 0
	v_pk_mul_f32 v[0:1], v[0:1], v[2:3]
	s_nop 0
	v_cvt_pk_bf16_f32 v11, v0, v1
	global_store_dwordx4 v[16:17], v[8:11], off nt
	s_cbranch_vccnz .LBB0_1092
	s_andn2_b64 vcc, exec, s[4:5]
	s_cbranch_vccnz .LBB0_1091
	s_barrier
	s_branch .LBB0_1091

.LBB0_1175:
	s_ashr_i32 s12, s53, 3
	v_lshl_or_b32 v134, s54, 8, v172
	s_mul_hi_i32 s13, s12, 0x9000
	s_mul_i32 s12, s12, 0x9000
	s_add_u32 s12, s46, s12
	v_ashrrev_i32_e32 v135, 31, v134
	s_addc_u32 s13, s47, s13
	v_lshlrev_b64 v[146:147], 2, v[134:135]
	v_lshl_add_u64 v[152:153], s[12:13], 0, v[146:147]
	global_load_dwordx4 v[134:137], v[152:153], off
	global_load_dwordx4 v[174:177], v[152:153], off offset:576
	s_mov_b64 s[12:13], -1
	s_and_b64 vcc, exec, s[0:1]
	s_movk_i32 s72, 0x2000
	s_mov_b32 s73, 0x14000
	s_waitcnt vmcnt(0)
	v_pk_mul_f32 v[148:149], v[136:137], 0.5 op_sel_hi:[1,0]
	v_pk_mul_f32 v[150:151], v[134:135], 0.5 op_sel_hi:[1,0]
	global_load_dwordx4 v[134:137], v[152:153], off offset:64
	s_waitcnt vmcnt(0)
	v_pk_mul_f32 v[142:143], v[136:137], 0.5 op_sel_hi:[1,0]
	v_pk_mul_f32 v[144:145], v[134:135], 0.5 op_sel_hi:[1,0]
	global_load_dwordx4 v[134:137], v[152:153], off offset:512
	v_lshl_add_u32 v152, s53, 8, v154
	v_ashrrev_i32_e32 v153, 31, v152
	s_waitcnt vmcnt(0)
	v_pk_mul_f32 v[138:139], v[136:137], 0.5 op_sel_hi:[1,0]
	v_pk_mul_f32 v[136:137], v[174:175], 0.5 op_sel_hi:[1,0]
	v_lshlrev_b64 v[174:175], 12, v[152:153]
	v_lshl_add_u64 v[174:175], s[26:27], 0, v[174:175]
	v_lshl_add_u64 v[180:181], v[174:175], 0, v[146:147]
	v_pk_mul_f32 v[140:141], v[134:135], 0.5 op_sel_hi:[1,0]
	v_pk_mul_f32 v[134:135], v[176:177], 0.5 op_sel_hi:[1,0]
	global_load_dwordx4 v[174:177], v[180:181], off
	global_load_dwordx4 v[188:191], v[180:181], off offset:64
	global_load_dwordx4 v[192:195], v[180:181], off offset:512
	global_load_dwordx4 v[196:199], v[180:181], off offset:576
	s_waitcnt vmcnt(0)
	v_pk_fma_f32 v[126:127], v[126:127], v[148:149], v[176:177]
	v_pk_fma_f32 v[124:125], v[124:125], v[150:151], v[174:175]
	global_store_dwordx4 v[180:181], v[124:127], off nt
	v_pk_fma_f32 v[122:123], v[122:123], v[142:143], v[190:191]
	v_pk_fma_f32 v[120:121], v[120:121], v[144:145], v[188:189]
	global_store_dwordx4 v[180:181], v[120:123], off offset:64 nt
	v_pk_fma_f32 v[118:119], v[118:119], v[138:139], v[194:195]
	v_pk_fma_f32 v[116:117], v[116:117], v[140:141], v[192:193]
	global_store_dwordx4 v[180:181], v[116:119], off offset:512 nt
	v_pk_fma_f32 v[114:115], v[114:115], v[134:135], v[198:199]
	v_pk_fma_f32 v[112:113], v[112:113], v[136:137], v[196:197]
	global_store_dwordx4 v[180:181], v[112:115], off offset:576 nt
	s_nop 1
	v_or_b32_e32 v112, 16, v152
	v_ashrrev_i32_e32 v113, 31, v112
	v_lshlrev_b64 v[112:113], 12, v[112:113]
	v_lshl_add_u64 v[112:113], s[26:27], 0, v[112:113]
	v_lshl_add_u64 v[116:117], v[112:113], 0, v[146:147]
	global_load_dwordx4 v[112:115], v[116:117], off
	global_load_dwordx4 v[188:191], v[116:117], off offset:64
	global_load_dwordx4 v[192:195], v[116:117], off offset:512
	global_load_dwordx4 v[196:199], v[116:117], off offset:576
	s_waitcnt vmcnt(0)
	v_pk_fma_f32 v[110:111], v[110:111], v[148:149], v[114:115]
	v_pk_fma_f32 v[108:109], v[108:109], v[150:151], v[112:113]
	global_store_dwordx4 v[116:117], v[108:111], off nt
	v_pk_fma_f32 v[106:107], v[106:107], v[142:143], v[190:191]
	v_pk_fma_f32 v[104:105], v[104:105], v[144:145], v[188:189]
	global_store_dwordx4 v[116:117], v[104:107], off offset:64 nt
	v_pk_fma_f32 v[102:103], v[102:103], v[138:139], v[194:195]
	v_pk_fma_f32 v[100:101], v[100:101], v[140:141], v[192:193]
	global_store_dwordx4 v[116:117], v[100:103], off offset:512 nt
	v_pk_fma_f32 v[98:99], v[98:99], v[134:135], v[198:199]
	v_pk_fma_f32 v[96:97], v[96:97], v[136:137], v[196:197]
	global_store_dwordx4 v[116:117], v[96:99], off offset:576 nt
	s_nop 1
	v_or_b32_e32 v96, 32, v152
	v_ashrrev_i32_e32 v97, 31, v96
	v_lshlrev_b64 v[96:97], 12, v[96:97]
	v_lshl_add_u64 v[96:97], s[26:27], 0, v[96:97]
	v_lshl_add_u64 v[100:101], v[96:97], 0, v[146:147]
	global_load_dwordx4 v[96:99], v[100:101], off
	global_load_dwordx4 v[188:191], v[100:101], off offset:64
	global_load_dwordx4 v[192:195], v[100:101], off offset:512
	global_load_dwordx4 v[196:199], v[100:101], off offset:576
	s_waitcnt vmcnt(0)
	v_pk_fma_f32 v[94:95], v[94:95], v[148:149], v[98:99]
	v_pk_fma_f32 v[92:93], v[92:93], v[150:151], v[96:97]
	global_store_dwordx4 v[100:101], v[92:95], off nt
	v_pk_fma_f32 v[90:91], v[90:91], v[142:143], v[190:191]
	v_pk_fma_f32 v[88:89], v[88:89], v[144:145], v[188:189]
	global_store_dwordx4 v[100:101], v[88:91], off offset:64 nt
	v_pk_fma_f32 v[86:87], v[86:87], v[138:139], v[194:195]
	v_pk_fma_f32 v[84:85], v[84:85], v[140:141], v[192:193]
	global_store_dwordx4 v[100:101], v[84:87], off offset:512 nt
	v_pk_fma_f32 v[82:83], v[82:83], v[134:135], v[198:199]
	v_pk_fma_f32 v[80:81], v[80:81], v[136:137], v[196:197]
	global_store_dwordx4 v[100:101], v[80:83], off offset:576 nt
	s_nop 1
	v_or_b32_e32 v80, 48, v152
	v_ashrrev_i32_e32 v81, 31, v80
	v_lshlrev_b64 v[80:81], 12, v[80:81]
	v_lshl_add_u64 v[80:81], s[26:27], 0, v[80:81]
	v_lshl_add_u64 v[84:85], v[80:81], 0, v[146:147]
	global_load_dwordx4 v[80:83], v[84:85], off
	global_load_dwordx4 v[188:191], v[84:85], off offset:64
	global_load_dwordx4 v[192:195], v[84:85], off offset:512
	global_load_dwordx4 v[196:199], v[84:85], off offset:576
	s_waitcnt vmcnt(0)
	v_pk_fma_f32 v[78:79], v[78:79], v[148:149], v[82:83]
	v_pk_fma_f32 v[76:77], v[76:77], v[150:151], v[80:81]
	global_store_dwordx4 v[84:85], v[76:79], off nt
	v_pk_fma_f32 v[74:75], v[74:75], v[142:143], v[190:191]
	v_pk_fma_f32 v[72:73], v[72:73], v[144:145], v[188:189]
	global_store_dwordx4 v[84:85], v[72:75], off offset:64 nt
	v_pk_fma_f32 v[70:71], v[70:71], v[138:139], v[194:195]
	v_pk_fma_f32 v[68:69], v[68:69], v[140:141], v[192:193]
	global_store_dwordx4 v[84:85], v[68:71], off offset:512 nt
	v_pk_fma_f32 v[66:67], v[66:67], v[134:135], v[198:199]
	v_pk_fma_f32 v[64:65], v[64:65], v[136:137], v[196:197]
	global_store_dwordx4 v[84:85], v[64:67], off offset:576 nt
	s_nop 1
	v_add_u32_e32 v64, 0x80, v152
	v_ashrrev_i32_e32 v65, 31, v64
	v_lshlrev_b64 v[64:65], 12, v[64:65]
	v_lshl_add_u64 v[64:65], s[26:27], 0, v[64:65]
	v_lshl_add_u64 v[68:69], v[64:65], 0, v[146:147]
	global_load_dwordx4 v[64:67], v[68:69], off
	global_load_dwordx4 v[188:191], v[68:69], off offset:64
	global_load_dwordx4 v[192:195], v[68:69], off offset:512
	global_load_dwordx4 v[196:199], v[68:69], off offset:576
	s_waitcnt vmcnt(0)
	v_pk_fma_f32 v[62:63], v[62:63], v[148:149], v[66:67]
	v_pk_fma_f32 v[60:61], v[60:61], v[150:151], v[64:65]
	global_store_dwordx4 v[68:69], v[60:63], off nt
	v_pk_fma_f32 v[58:59], v[58:59], v[142:143], v[190:191]
	v_pk_fma_f32 v[56:57], v[56:57], v[144:145], v[188:189]
	global_store_dwordx4 v[68:69], v[56:59], off offset:64 nt
	v_pk_fma_f32 v[54:55], v[54:55], v[138:139], v[194:195]
	v_pk_fma_f32 v[52:53], v[52:53], v[140:141], v[192:193]
	global_store_dwordx4 v[68:69], v[52:55], off offset:512 nt
	v_pk_fma_f32 v[50:51], v[50:51], v[134:135], v[198:199]
	v_pk_fma_f32 v[48:49], v[48:49], v[136:137], v[196:197]
	global_store_dwordx4 v[68:69], v[48:51], off offset:576 nt
	s_nop 1
	v_add_u32_e32 v48, 0x90, v152
	v_ashrrev_i32_e32 v49, 31, v48
	v_lshlrev_b64 v[48:49], 12, v[48:49]
	v_lshl_add_u64 v[48:49], s[26:27], 0, v[48:49]
	v_lshl_add_u64 v[52:53], v[48:49], 0, v[146:147]
	global_load_dwordx4 v[48:51], v[52:53], off
	global_load_dwordx4 v[188:191], v[52:53], off offset:64
	global_load_dwordx4 v[192:195], v[52:53], off offset:512
	global_load_dwordx4 v[196:199], v[52:53], off offset:576
	s_waitcnt vmcnt(0)
	v_pk_fma_f32 v[46:47], v[46:47], v[148:149], v[50:51]
	v_pk_fma_f32 v[44:45], v[44:45], v[150:151], v[48:49]
	global_store_dwordx4 v[52:53], v[44:47], off nt
	v_pk_fma_f32 v[42:43], v[42:43], v[142:143], v[190:191]
	v_pk_fma_f32 v[40:41], v[40:41], v[144:145], v[188:189]
	global_store_dwordx4 v[52:53], v[40:43], off offset:64 nt
	v_pk_fma_f32 v[38:39], v[38:39], v[138:139], v[194:195]
	v_pk_fma_f32 v[36:37], v[36:37], v[140:141], v[192:193]
	global_store_dwordx4 v[52:53], v[36:39], off offset:512 nt
	v_pk_fma_f32 v[34:35], v[34:35], v[134:135], v[198:199]
	v_pk_fma_f32 v[32:33], v[32:33], v[136:137], v[196:197]
	global_store_dwordx4 v[52:53], v[32:35], off offset:576 nt
	s_nop 1
	v_add_u32_e32 v32, 0xa0, v152
	v_ashrrev_i32_e32 v33, 31, v32
	v_lshlrev_b64 v[32:33], 12, v[32:33]
	v_lshl_add_u64 v[32:33], s[26:27], 0, v[32:33]
	v_lshl_add_u64 v[36:37], v[32:33], 0, v[146:147]
	global_load_dwordx4 v[32:35], v[36:37], off
	global_load_dwordx4 v[188:191], v[36:37], off offset:64
	global_load_dwordx4 v[192:195], v[36:37], off offset:512
	global_load_dwordx4 v[196:199], v[36:37], off offset:576
	s_waitcnt vmcnt(0)
	v_pk_fma_f32 v[30:31], v[30:31], v[148:149], v[34:35]
	v_pk_fma_f32 v[28:29], v[28:29], v[150:151], v[32:33]
	global_store_dwordx4 v[36:37], v[28:31], off nt
	v_pk_fma_f32 v[26:27], v[26:27], v[142:143], v[190:191]
	v_pk_fma_f32 v[24:25], v[24:25], v[144:145], v[188:189]
	global_store_dwordx4 v[36:37], v[24:27], off offset:64 nt
	v_pk_fma_f32 v[22:23], v[22:23], v[138:139], v[194:195]
	v_pk_fma_f32 v[20:21], v[20:21], v[140:141], v[192:193]
	global_store_dwordx4 v[36:37], v[20:23], off offset:512 nt
	v_pk_fma_f32 v[18:19], v[18:19], v[134:135], v[198:199]
	v_pk_fma_f32 v[16:17], v[16:17], v[136:137], v[196:197]
	global_store_dwordx4 v[36:37], v[16:19], off offset:576 nt
	s_nop 1
	v_add_u32_e32 v16, 0xb0, v152
	v_ashrrev_i32_e32 v17, 31, v16
	v_lshlrev_b64 v[16:17], 12, v[16:17]
	v_lshl_add_u64 v[16:17], s[26:27], 0, v[16:17]
	v_lshl_add_u64 v[16:17], v[16:17], 0, v[146:147]
	global_load_dwordx4 v[18:21], v[16:17], off
	global_load_dwordx4 v[188:191], v[16:17], off offset:64
	global_load_dwordx4 v[192:195], v[16:17], off offset:512
	global_load_dwordx4 v[196:199], v[16:17], off offset:576
	s_waitcnt vmcnt(0)
	v_pk_fma_f32 v[14:15], v[14:15], v[148:149], v[20:21]
	v_pk_fma_f32 v[12:13], v[12:13], v[150:151], v[18:19]
	global_store_dwordx4 v[16:17], v[12:15], off nt
	v_pk_fma_f32 v[10:11], v[10:11], v[142:143], v[190:191]
	v_pk_fma_f32 v[8:9], v[8:9], v[144:145], v[188:189]
	global_store_dwordx4 v[16:17], v[8:11], off offset:64 nt
	v_pk_fma_f32 v[6:7], v[6:7], v[138:139], v[194:195]
	v_pk_fma_f32 v[4:5], v[4:5], v[140:141], v[192:193]
	global_store_dwordx4 v[16:17], v[4:7], off offset:512 nt
	v_pk_fma_f32 v[2:3], v[2:3], v[134:135], v[198:199]
	v_pk_fma_f32 v[0:1], v[0:1], v[136:137], v[196:197]
	global_store_dwordx4 v[16:17], v[0:3], off offset:576 nt
	s_cbranch_vccnz .LBB0_1160
	s_andn2_b64 vcc, exec, s[6:7]
	s_cbranch_vccnz .LBB0_1159
	s_barrier
	s_branch .LBB0_1159
